# LN+gate-logit phases: next-row prefetch, gate bias loaded once per phase, packed-FMA dot products with weight quads streamed through a register buffer, transpose-reduce of the 8 logits
# speedup vs baseline: 1.0122x; 1.0054x over previous
; __device__ __forceinline__ int mk_tid(int wv) { return (wv << 6) | lane_now(); }
; #define LAS __attribute__((address_space(3)))
; template <int SRC, int EXTRA, bool OUT8 = false> ...
;     const int tid = mk_tid(wv); const int lane = tid & 63, wave = wv;
;     LAS float* w8s = (LAS float*)lds;
;     LAS unsigned* lcnt = (LAS unsigned*)(lds + 32768);
;     if (EXTRA != 0) { for (int i = tid; i < 8192; i += NT) { const int k = i >> 3, j = i & 7; w8s[j * 1024 + k] = w8[(size_t)k * w8ld + j]; } if (tid < 8) lcnt[tid] = 0u; __syncthreads(); }
;     f32x4 gv[4], bv[4];
; #pragma unroll
;     for (int j = 0; j < 4; ++j) { gv[j] = *(const f32x4*)(g + 256 * j + 4 * lane); bv[j] = *(const f32x4*)(b + 256 * j + 4 * lane); }
;     const int gw = blockIdx.x * NWAVES + wave, NGW = G * NWAVES;
;     for (int row = gw; row < M; row += NGW) {
.LBB0_53:
	s_or_b64 exec, exec, s[12:13]
	v_cmp_gt_i32_e32 vcc, 8, v2
	s_and_saveexec_b64 s[12:13], vcc
	v_lshl_add_u32 v2, v2, 2, 0
	v_mov_b32_e32 v3, 0
	ds_write_b32 v2, v3 offset:32768
	s_or_b64 exec, exec, s[12:13]
	s_lshl_b32 s3, s2, 3
	s_add_i32 s34, s68, s3
	s_cmpk_lt_i32 s34, 0x4000
	s_cselect_b64 s[38:39], -1, 0
	s_cmpk_gt_i32 s34, 0x3fff
	s_waitcnt lgkmcnt(0)
	s_barrier
	s_cbranch_scc1 .LBB0_66
	v_and_b32_e32 v36, 63, v8
	v_lshlrev_b32_e32 v50, 4, v36
	global_load_dwordx4 v[2:5], v50, s[4:5]
	global_load_dwordx4 v[6:9], v50, s[4:5] offset:1024
	global_load_dwordx4 v[10:13], v50, s[8:9]
	global_load_dwordx4 v[14:17], v50, s[8:9] offset:1024
	global_load_dwordx4 v[18:21], v50, s[4:5] offset:2048
	global_load_dwordx4 v[22:25], v50, s[4:5] offset:3072
	global_load_dwordx4 v[26:29], v50, s[8:9] offset:2048
	global_load_dwordx4 v[30:33], v50, s[8:9] offset:3072
	s_add_u32 s3, s6, 0x400000
	s_addc_u32 s44, s7, 0
	s_lshl_b32 s26, s2, 4
	s_lshl_b32 s27, s68, 1
	s_ashr_i32 s35, s34, 31
	s_add_i32 s26, s26, s27
	s_lshl_b32 s45, s33, 4
	s_lshl_b64 s[40:41], s[34:35], 2
	v_lshlrev_b32_e32 v52, 2, v36
	v_mov_b32_e32 v53, 0
	s_add_u32 s28, s28, s40
	v_lshl_add_u64 v[54:55], s[10:11], 0, v[52:53]
	v_lshlrev_b32_e32 v52, 16, v36
	s_addc_u32 s29, s29, s41
	v_lshl_add_u64 v[34:35], s[28:29], 0, v[52:53]
	s_mov_b64 s[28:29], 0x100000
	s_ashr_i32 s31, s30, 31
	v_lshl_add_u64 v[56:57], v[34:35], 0, s[28:29]
	s_lshl_b64 s[28:29], s[30:31], 2
	s_lshl_b64 s[40:41], s[34:35], 11
	s_add_u32 s36, s36, s40
	v_lshlrev_b32_e32 v52, 3, v36
	s_addc_u32 s37, s37, s41
	v_lshl_add_u64 v[34:35], s[36:37], 0, v[52:53]
	s_mov_b64 s[36:37], 0x12500000
	v_lshl_add_u64 v[58:59], v[34:35], 0, s[36:37]
	s_lshl_b64 s[36:37], s[30:31], 11
	s_lshl_b64 s[40:41], s[34:35], 12
	s_add_u32 s22, s22, s40
	v_mov_b32_e32 v51, v53
	s_addc_u32 s23, s23, s41
	v_lshl_add_u64 v[34:35], s[22:23], 0, v[50:51]
	s_mov_b64 s[22:23], 0xc00
	v_cmp_eq_u32_e64 s[4:5], 0, v36
	v_cmp_gt_u32_e64 s[6:7], 8, v36
	v_cmp_eq_u32_e64 s[8:9], 7, v36
	v_cmp_eq_u32_e64 s[10:11], 6, v36
	v_cmp_eq_u32_e64 s[12:13], 5, v36
	v_cmp_eq_u32_e64 s[14:15], 4, v36
	v_cmp_eq_u32_e64 s[16:17], 3, v36
	v_cmp_eq_u32_e64 s[18:19], 2, v36
	v_cmp_eq_u32_e64 s[20:21], 1, v36
	v_lshl_add_u64 v[60:61], v[34:35], 0, s[22:23]
	s_lshl_b64 s[40:41], s[30:31], 12
	v_mov_b32_e32 v51, 0x3727c5ac
	s_mov_b32 s31, 0xf800000
	v_mov_b32_e32 v68, 0x260
	s_movk_i32 s35, 0x7fff
	s_mov_b32 s46, 0xffff0000
	s_mov_b32 s47, 0x3f2aaaab
	v_mov_b32_e32 v69, 0x3ecc95a3
	s_mov_b32 s48, 0x3f317218
	s_mov_b32 s49, 0x7f800000
	s_mov_b32 s50, 0x33800000
	v_mov_b32_e32 v62, 0x3f317218
	v_mov_b32_e32 v70, 0x7f800000
	v_mov_b32_e32 v71, 0x7fc00000
	v_mov_b32_e32 v72, 0xff800000
	s_mov_b32 s51, s34
	global_load_dwordx4 v[200:203], v[60:61], off offset:-3072
	global_load_dwordx4 v[196:199], v[60:61], off offset:-2048
	global_load_dwordx4 v[192:195], v[60:61], off offset:-1024
	global_load_dwordx4 v[188:191], v[60:61], off
	s_waitcnt vmcnt(0)
	s_mov_b32 s58, 0xaaaaaaaa
	s_mov_b32 s59, 0xaaaaaaaa
	s_mov_b32 s60, 0xcccccccc
	s_mov_b32 s61, 0xcccccccc
	s_mov_b32 s62, 0xf0f0f0f0
	s_mov_b32 s63, 0xf0f0f0f0
	v_mov_b32_e32 v206, 0
	s_and_saveexec_b64 s[66:67], s[6:7]
	global_load_dword v206, v[54:55], off
	s_or_b64 exec, exec, s[66:67]
	s_waitcnt vmcnt(0)
	s_branch .LBB0_59

; template <int SRC, int EXTRA, bool OUT8 = false> ...
;     ...
;     for (int row = gw; row < M; row += NGW) {
;         f32x4 v[4];
;         if (SRC == 0) {
; #pragma unroll
;             for (int j = 0; j < 4; ++j) v[j] = *(const f32x4*)(src + (size_t)row * 1024 + 256 * j + 4 * lane);
;         } else {
;             const int p0 = pos[2 * row], p1 = pos[2 * row + 1]; const float w0 = gwt[2 * row], w1 = gwt[2 * row + 1]; const float hm = hp.stats[2 * row], hr = hp.stats[2 * row + 1];
; #pragma unroll
;             for (int j = 0; j < 4; ++j) { const f32x4 a = (*(const f32x4*)(hp.src + (size_t)row * 1024 + 256 * j + 4 * lane) - hm) * hr * *(const f32x4*)(hp.g + 256 * j + 4 * lane) + *(const f32x4*)(hp.b + 256 * j + 4 * lane);
;                 f32x4 y[2];
; #pragma unroll
;                 for (int q = 0; q < 2; ++q) { const int p = q ? p1 : p0; const int t = __builtin_amdgcn_readfirstlane(tailid[(p >> 8) * 4 + j]);
;                     if (t < 0) y[q] = *(const f32x4*)(ys + (size_t)p * 1024 + 256 * j + 4 * lane);
;                     else { f32x4 acc = (f32x4){0.f, 0.f, 0.f, 0.f};
; #pragma unroll
;                         for (int sl = 0; sl < 7; ++sl) acc = acc + *(const f32x4*)(part + ((size_t)(t * 7 + sl) * 256 + (p & 255)) * 256 + 4 * lane);
;                         y[q] = acc; } }
;                 v[j] = a * ALPHA + y[0] * w0 + y[1] * w1; }
;         }
;         float s = 0.f;
; #pragma unroll
;         for (int j = 0; j < 4; ++j) s += (v[j].x + v[j].y) + (v[j].z + v[j].w);
;         const float mean = wave_sum(s) * (1.f / 1024.f); float s2 = 0.f;
; #pragma unroll
;         for (int j = 0; j < 4; ++j) { v[j] = v[j] - mean; s2 += (v[j].x * v[j].x + v[j].y * v[j].y) + (v[j].z * v[j].z + v[j].w * v[j].w); }
;         const float rstd = 1.f / sqrtf(wave_sum(s2) * (1.f / 1024.f) + LN_EPS);
;         if (stats && lane == 0) { stats[2 * row] = mean; stats[2 * row + 1] = rstd; }
.LBB0_59:
	s_waitcnt vmcnt(1)
	v_mov_b64_e32 v[34:35], v[188:189]
	v_mov_b64_e32 v[36:37], v[190:191]
	v_mov_b64_e32 v[38:39], v[192:193]
	v_mov_b64_e32 v[40:41], v[194:195]
	v_mov_b64_e32 v[42:43], v[196:197]
	v_mov_b64_e32 v[44:45], v[198:199]
	v_mov_b64_e32 v[46:47], v[200:201]
	v_mov_b64_e32 v[48:49], v[202:203]
	s_add_i32 s95, s51, s30
	s_cmpk_lt_i32 s95, 0x4000
	s_cbranch_scc0 .Lrowpf_2726
	v_lshl_add_u64 v[204:205], v[60:61], 0, s[40:41]
	global_load_dwordx4 v[200:203], v[204:205], off offset:-3072
	global_load_dwordx4 v[196:199], v[204:205], off offset:-2048
	global_load_dwordx4 v[192:195], v[204:205], off offset:-1024
	global_load_dwordx4 v[188:191], v[204:205], off
.Lrowpf_2726:
	s_waitcnt lgkmcnt(0)
	ds_read_b128 v[124:127], v50
	ds_read_b128 v[128:131], v50 offset:1024
	ds_read_b128 v[132:135], v50 offset:2048
	ds_read_b128 v[136:139], v50 offset:3072
	ds_read_b128 v[140:143], v50 offset:4096
	ds_read_b128 v[144:147], v50 offset:5120
	ds_read_b128 v[148:151], v50 offset:6144
	ds_read_b128 v[152:155], v50 offset:7168
	ds_read_b128 v[156:159], v50 offset:8192
	ds_read_b128 v[160:163], v50 offset:9216
	ds_read_b128 v[164:167], v50 offset:10240
	ds_read_b128 v[168:171], v50 offset:11264
	ds_read_b128 v[172:175], v50 offset:12288
	ds_read_b128 v[176:179], v50 offset:13312
	ds_read_b128 v[180:183], v50 offset:14336
	ds_read_b128 v[184:187], v50 offset:15360
	v_mov_b32_e32 v64, v47
	v_mov_b32_e32 v65, v48
	v_mov_b32_e32 v66, v46
	v_mov_b32_e32 v67, v49
	v_mov_b32_e32 v74, v43
	v_mov_b32_e32 v75, v44
	v_mov_b32_e32 v76, v42
	v_mov_b32_e32 v77, v45
	v_pk_add_f32 v[64:65], v[64:65], v[66:67]
	v_pk_add_f32 v[66:67], v[74:75], v[76:77]
	v_add_f32_e32 v63, v64, v65
	v_pk_add_f32 v[64:65], v[66:67], v[66:67] op_sel:[0,1] op_sel_hi:[1,0]
	v_add_f32_e32 v78, v38, v39
	v_add_f32_e32 v80, v40, v41
	v_mov_b32_e32 v83, v34
	v_mov_b32_e32 v79, v36
	v_mov_b32_e32 v81, v37
	v_add_f32_e32 v82, 0, v63
	v_mov_b32_e32 v65, v35
	v_pk_add_f32 v[74:75], v[78:79], v[80:81]
	v_pk_add_f32 v[64:65], v[82:83], v[64:65]
	v_pk_add_f32 v[64:65], v[64:65], v[74:75]
	v_add_f32_e32 v63, v64, v65
	s_nop 1
	v_mov_b32_dpp v52, v63 quad_perm:[1,0,3,2] row_mask:0xf bank_mask:0xf
	v_add_f32_e32 v52, v63, v52
	s_nop 1
	v_mov_b32_dpp v63, v52 quad_perm:[2,3,0,1] row_mask:0xf bank_mask:0xf
	v_add_f32_e32 v52, v52, v63
	s_nop 1
	v_mov_b32_dpp v63, v52 row_shl:4 row_mask:0xf bank_mask:0x5
	v_mov_b32_dpp v63, v52 row_shr:4 row_mask:0xf bank_mask:0xa
	v_add_f32_e32 v52, v52, v63
	s_nop 1
	v_mov_b32_dpp v63, v52 row_ror:8 row_mask:0xf bank_mask:0xf
	v_add_f32_e32 v52, v52, v63
	v_mov_b32_e32 v63, v52
	v_mov_b32_e32 v120, v52
	s_nop 1
	v_permlane16_swap_b32_e32 v63, v120
	v_cndmask_b32_e64 v63, v120, v63, s[98:99]
	v_add_f32_e32 v52, v52, v63
	v_mov_b32_e32 v63, v52
	v_mov_b32_e32 v120, v52
	s_nop 1
	v_permlane32_swap_b32_e32 v63, v120
	v_cndmask_b32_e64 v63, v120, v63, s[100:101]
	v_add_f32_e32 v63, v52, v63
	v_fmamk_f32 v67, v63, 0xba800000, v49
	v_fmamk_f32 v47, v63, 0xba800000, v47
	v_fmamk_f32 v45, v63, 0xba800000, v45
	v_fmamk_f32 v43, v63, 0xba800000, v43
	v_fmamk_f32 v66, v63, 0xba800000, v48
	v_fmac_f32_e32 v46, 0xba800000, v63
	v_fmamk_f32 v44, v63, 0xba800000, v44
	v_fmac_f32_e32 v42, 0xba800000, v63
	v_fmamk_f32 v65, v63, 0xba800000, v41
	v_fmamk_f32 v64, v63, 0xba800000, v40
	v_fmamk_f32 v39, v63, 0xba800000, v39
	v_fmamk_f32 v49, v63, 0xba800000, v37
	v_fmamk_f32 v48, v63, 0xba800000, v36
	v_mul_f32_e32 v36, v47, v47
	v_mul_f32_e32 v37, v67, v67
	v_mul_f32_e32 v40, v43, v43
	v_mul_f32_e32 v41, v45, v45
	v_fmac_f32_e32 v38, 0xba800000, v63
	v_fmamk_f32 v35, v63, 0xba800000, v35
	v_mul_f32_e32 v52, v39, v39
	v_mul_f32_e32 v74, v65, v65
	v_fmac_f32_e32 v36, v46, v46
	v_fmac_f32_e32 v37, v66, v66
	v_fmac_f32_e32 v40, v42, v42
	v_fmac_f32_e32 v41, v44, v44
	v_fmac_f32_e32 v34, 0xba800000, v63
	v_mul_f32_e32 v75, v35, v35
	v_mul_f32_e32 v76, v49, v49
	v_fmac_f32_e32 v52, v38, v38
	v_fmac_f32_e32 v74, v64, v64
	v_add_f32_e32 v36, v36, v37
	v_add_f32_e32 v37, v40, v41
	v_fmac_f32_e32 v75, v34, v34
	v_fmac_f32_e32 v76, v48, v48
	v_add_f32_e32 v40, v52, v74
	v_add_f32_e32 v36, v36, v37
	v_add_f32_e32 v41, v75, v76
	v_add_f32_e32 v36, v40, v36
	v_add_f32_e32 v36, v41, v36
	s_nop 1
	v_mov_b32_dpp v37, v36 quad_perm:[1,0,3,2] row_mask:0xf bank_mask:0xf
	v_add_f32_e32 v36, v36, v37
	s_nop 1
	v_mov_b32_dpp v37, v36 quad_perm:[2,3,0,1] row_mask:0xf bank_mask:0xf
	v_add_f32_e32 v36, v36, v37
	s_nop 1
	v_mov_b32_dpp v37, v36 row_shl:4 row_mask:0xf bank_mask:0x5
	v_mov_b32_dpp v37, v36 row_shr:4 row_mask:0xf bank_mask:0xa
	v_add_f32_e32 v36, v36, v37
	s_nop 1
	v_mov_b32_dpp v37, v36 row_ror:8 row_mask:0xf bank_mask:0xf
	v_add_f32_e32 v36, v36, v37
	v_mov_b32_e32 v37, v36
	v_mov_b32_e32 v120, v36
	s_nop 1
	v_permlane16_swap_b32_e32 v37, v120
	v_cndmask_b32_e64 v37, v120, v37, s[98:99]
	v_add_f32_e32 v36, v36, v37
	v_mov_b32_e32 v37, v36
	v_mov_b32_e32 v120, v36
	s_nop 1
	v_permlane32_swap_b32_e32 v37, v120
	v_cndmask_b32_e64 v37, v120, v37, s[100:101]
	v_add_f32_e32 v36, v36, v37
	v_fmamk_f32 v36, v36, 0x3a800000, v51
	v_mul_f32_e32 v37, 0x4f800000, v36
	v_cmp_gt_f32_e32 vcc, s31, v36
	s_nop 1
	v_cndmask_b32_e32 v36, v36, v37, vcc
	v_sqrt_f32_e32 v37, v36
	s_nop 0
	v_add_u32_e32 v40, -1, v37
	v_add_u32_e32 v41, 1, v37
	v_fma_f32 v52, -v40, v37, v36
	v_fma_f32 v73, -v41, v37, v36
	v_cmp_ge_f32_e64 s[22:23], 0, v52
	s_nop 1
	v_cndmask_b32_e64 v37, v37, v40, s[22:23]
	v_cmp_lt_f32_e64 s[22:23], 0, v73
	s_nop 1
	v_cndmask_b32_e64 v37, v37, v41, s[22:23]
	v_mul_f32_e32 v40, 0x37800000, v37
	v_cndmask_b32_e32 v37, v37, v40, vcc
	v_cmp_class_f32_e32 vcc, v36, v68
	s_nop 1
	v_cndmask_b32_e32 v36, v37, v36, vcc
	v_div_scale_f32 v37, s[22:23], v36, v36, 1.0
	v_rcp_f32_e32 v40, v37
	v_div_scale_f32 v41, vcc, 1.0, v36, 1.0
	v_fma_f32 v52, -v37, v40, 1.0
	v_fmac_f32_e32 v40, v52, v40
	v_mul_f32_e32 v52, v41, v40
	v_fma_f32 v73, -v37, v52, v41
	v_fmac_f32_e32 v52, v73, v40
	v_fma_f32 v37, -v37, v52, v41
	v_div_fmas_f32 v37, v37, v40, v52
	v_div_fixup_f32 v52, v37, v36, 1.0
	s_and_saveexec_b64 s[22:23], s[4:5]
	s_cbranch_execz .LBB0_61
	s_ashr_i32 s27, s26, 31
	s_lshl_b64 s[42:43], s[26:27], 2
	s_add_u32 s42, s3, s42
	v_mul_f32_e32 v36, 0x3a800000, v63
	s_addc_u32 s43, s44, s43
	v_mov_b32_e32 v37, v52
	global_store_dwordx2 v53, v[36:37], s[42:43]
; #define LAS __attribute__((address_space(3)))
; __device__ __forceinline__ unsigned pk2(float lo, float hi) { return f2bf(lo) | (f2bf(hi) << 16); }
; template <int SRC, int EXTRA, bool OUT8 = false> ...
;     ...
;         if (stats && lane == 0) { stats[2 * row] = mean; stats[2 * row + 1] = rstd; }
; #pragma unroll
;         for (int j = 0; j < 4; ++j) { v[j] = v[j] * rstd * gv[j] + bv[j]; if (of32) *(f32x4*)(of32 + (size_t)row * 1024 + 256 * j + 4 * lane) = v[j];
;             if (obf) { if constexpr (OUT8) { int w = 0; w = __builtin_amdgcn_cvt_pk_fp8_f32(v[j].x, v[j].y, w, false); w = __builtin_amdgcn_cvt_pk_fp8_f32(v[j].z, v[j].w, w, true); *(unsigned*)((unsigned char*)obf + (size_t)row * 1024 + 256 * j + 4 * lane) = (unsigned)w; }
;                 else { v2u o; o.x = pk2(v[j].x, v[j].y); o.y = pk2(v[j].z, v[j].w); *(v2u*)(obf + (size_t)row * 1024 + 256 * j + 4 * lane) = o; } } }
;         if (EXTRA != 0) {
;             float d[8];
; #pragma unroll
;             for (int e = 0; e < 8; ++e) { float a = 0.f;
; #pragma unroll
;                 for (int j = 0; j < 4; ++j) { const f32x4 w = *(const LAS f32x4*)(w8s + e * 1024 + 256 * j + 4 * lane); a += (v[j].x * w.x + v[j].y * w.y) + (v[j].z * w.z + v[j].w * w.w); }
;                 d[e] = wave_sum(a); }
.LBB0_61:
	s_or_b64 exec, exec, s[22:23]
	v_pk_mul_f32 v[40:41], v[46:47], v[52:53] op_sel_hi:[1,0]
	v_pk_mul_f32 v[36:37], v[66:67], v[52:53] op_sel_hi:[1,0]
	v_pk_fma_f32 v[40:41], v[2:3], v[40:41], v[10:11]
	v_pk_fma_f32 v[36:37], v[4:5], v[36:37], v[12:13]
	v_bfe_u32 v46, v40, 16, 1
	v_add3_u32 v46, v40, v46, s35
	v_bfe_u32 v47, v41, 16, 1
	v_lshrrev_b32_e32 v46, 16, v46
	v_add3_u32 v47, v41, v47, s35
	v_and_or_b32 v46, v47, s46, v46
	v_bfe_u32 v47, v36, 16, 1
	v_add3_u32 v47, v36, v47, s35
	v_bfe_u32 v63, v37, 16, 1
	v_lshrrev_b32_e32 v47, 16, v47
	v_add3_u32 v63, v37, v63, s35
	v_and_or_b32 v47, v63, s46, v47
	global_store_dwordx2 v[58:59], v[46:47], off
	v_pk_mul_f32 v[44:45], v[44:45], v[52:53] op_sel_hi:[1,0]
	v_pk_mul_f32 v[46:47], v[42:43], v[52:53] op_sel_hi:[1,0]
	v_pk_fma_f32 v[42:43], v[8:9], v[44:45], v[16:17]
	v_pk_fma_f32 v[44:45], v[6:7], v[46:47], v[14:15]
	v_bfe_u32 v63, v43, 16, 1
	v_bfe_u32 v46, v44, 16, 1
	v_add3_u32 v46, v44, v46, s35
	v_bfe_u32 v47, v45, 16, 1
	v_lshrrev_b32_e32 v46, 16, v46
	v_add3_u32 v47, v45, v47, s35
	v_and_or_b32 v46, v47, s46, v46
	v_bfe_u32 v47, v42, 16, 1
	v_add3_u32 v47, v42, v47, s35
	v_lshrrev_b32_e32 v47, 16, v47
	v_add3_u32 v63, v43, v63, s35
	v_and_or_b32 v47, v63, s46, v47
	global_store_dwordx2 v[58:59], v[46:47], off offset:512
	v_pk_mul_f32 v[46:47], v[64:65], v[52:53] op_sel_hi:[1,0]
	v_pk_mul_f32 v[64:65], v[38:39], v[52:53] op_sel_hi:[1,0]
	v_pk_fma_f32 v[38:39], v[20:21], v[46:47], v[28:29]
	v_pk_fma_f32 v[46:47], v[18:19], v[64:65], v[26:27]
	v_bfe_u32 v65, v39, 16, 1
	v_bfe_u32 v63, v46, 16, 1
	v_add3_u32 v63, v46, v63, s35
	v_bfe_u32 v64, v47, 16, 1
	v_lshrrev_b32_e32 v63, 16, v63
	v_add3_u32 v64, v47, v64, s35
	v_and_or_b32 v64, v64, s46, v63
	v_bfe_u32 v63, v38, 16, 1
	v_add3_u32 v63, v38, v63, s35
	v_lshrrev_b32_e32 v63, 16, v63
	v_add3_u32 v65, v39, v65, s35
	v_and_or_b32 v65, v65, s46, v63
	global_store_dwordx2 v[58:59], v[64:65], off offset:1024
	v_pk_mul_f32 v[48:49], v[48:49], v[52:53] op_sel_hi:[1,0]
	v_pk_mul_f32 v[64:65], v[34:35], v[52:53] op_sel_hi:[1,0]
	v_pk_fma_f32 v[34:35], v[24:25], v[48:49], v[32:33]
	v_pk_fma_f32 v[48:49], v[22:23], v[64:65], v[30:31]
	v_bfe_u32 v73, v35, 16, 1
	v_bfe_u32 v52, v48, 16, 1
	v_add3_u32 v52, v48, v52, s35
	v_bfe_u32 v63, v49, 16, 1
	v_lshrrev_b32_e32 v52, 16, v52
	v_add3_u32 v63, v49, v63, s35
	v_and_or_b32 v74, v63, s46, v52
	v_bfe_u32 v52, v34, 16, 1
	v_add3_u32 v52, v34, v52, s35
	v_lshrrev_b32_e32 v63, 16, v52
	v_add_u32_e32 v52, 0, v50
	v_add3_u32 v73, v35, v73, s35
	v_and_or_b32 v75, v73, s46, v63
	global_store_dwordx2 v[58:59], v[74:75], off offset:1536
	s_waitcnt lgkmcnt(0)
	v_pk_mul_f32 v[104:105], v[40:41], v[124:125]
	v_pk_mul_f32 v[106:107], v[40:41], v[140:141]
	v_pk_mul_f32 v[108:109], v[40:41], v[156:157]
	v_pk_mul_f32 v[110:111], v[40:41], v[172:173]
	v_pk_fma_f32 v[104:105], v[36:37], v[126:127], v[104:105]
	v_pk_fma_f32 v[106:107], v[36:37], v[142:143], v[106:107]
	v_pk_fma_f32 v[108:109], v[36:37], v[158:159], v[108:109]
	v_pk_fma_f32 v[110:111], v[36:37], v[174:175], v[110:111]
	ds_read_b128 v[124:127], v50 offset:16384
	ds_read_b128 v[140:143], v50 offset:20480
	ds_read_b128 v[156:159], v50 offset:24576
	ds_read_b128 v[172:175], v50 offset:28672
	v_pk_fma_f32 v[104:105], v[44:45], v[128:129], v[104:105]
	v_pk_fma_f32 v[106:107], v[44:45], v[144:145], v[106:107]
	v_pk_fma_f32 v[108:109], v[44:45], v[160:161], v[108:109]
	v_pk_fma_f32 v[110:111], v[44:45], v[176:177], v[110:111]
	v_pk_fma_f32 v[104:105], v[42:43], v[130:131], v[104:105]
	v_pk_fma_f32 v[106:107], v[42:43], v[146:147], v[106:107]
	v_pk_fma_f32 v[108:109], v[42:43], v[162:163], v[108:109]
	v_pk_fma_f32 v[110:111], v[42:43], v[178:179], v[110:111]
	ds_read_b128 v[128:131], v50 offset:17408
	ds_read_b128 v[144:147], v50 offset:21504
	ds_read_b128 v[160:163], v50 offset:25600
	ds_read_b128 v[176:179], v50 offset:29696
	v_pk_fma_f32 v[104:105], v[46:47], v[132:133], v[104:105]
	v_pk_fma_f32 v[106:107], v[46:47], v[148:149], v[106:107]
	v_pk_fma_f32 v[108:109], v[46:47], v[164:165], v[108:109]
	v_pk_fma_f32 v[110:111], v[46:47], v[180:181], v[110:111]
	v_pk_fma_f32 v[104:105], v[38:39], v[134:135], v[104:105]
	v_pk_fma_f32 v[106:107], v[38:39], v[150:151], v[106:107]
	v_pk_fma_f32 v[108:109], v[38:39], v[166:167], v[108:109]
	v_pk_fma_f32 v[110:111], v[38:39], v[182:183], v[110:111]
	ds_read_b128 v[132:135], v50 offset:18432
	ds_read_b128 v[148:151], v50 offset:22528
	ds_read_b128 v[164:167], v50 offset:26624
	ds_read_b128 v[180:183], v50 offset:30720
	v_pk_fma_f32 v[104:105], v[48:49], v[136:137], v[104:105]
	v_pk_fma_f32 v[106:107], v[48:49], v[152:153], v[106:107]
	v_pk_fma_f32 v[108:109], v[48:49], v[168:169], v[108:109]
	v_pk_fma_f32 v[110:111], v[48:49], v[184:185], v[110:111]
	v_pk_fma_f32 v[104:105], v[34:35], v[138:139], v[104:105]
	v_pk_fma_f32 v[106:107], v[34:35], v[154:155], v[106:107]
	v_pk_fma_f32 v[108:109], v[34:35], v[170:171], v[108:109]
	v_pk_fma_f32 v[110:111], v[34:35], v[186:187], v[110:111]
	ds_read_b128 v[136:139], v50 offset:19456
	ds_read_b128 v[152:155], v50 offset:23552
	ds_read_b128 v[168:171], v50 offset:27648
	ds_read_b128 v[184:187], v50 offset:31744
	v_add_f32_e32 v96, v104, v105
	v_add_f32_e32 v97, v106, v107
	v_add_f32_e32 v98, v108, v109
	v_add_f32_e32 v99, v110, v111
	s_waitcnt lgkmcnt(12)
	v_pk_mul_f32 v[104:105], v[40:41], v[124:125]
	v_pk_mul_f32 v[106:107], v[40:41], v[140:141]
	v_pk_mul_f32 v[108:109], v[40:41], v[156:157]
	v_pk_mul_f32 v[110:111], v[40:41], v[172:173]
	v_pk_fma_f32 v[104:105], v[36:37], v[126:127], v[104:105]
	v_pk_fma_f32 v[106:107], v[36:37], v[142:143], v[106:107]
	v_pk_fma_f32 v[108:109], v[36:37], v[158:159], v[108:109]
	v_pk_fma_f32 v[110:111], v[36:37], v[174:175], v[110:111]
	s_waitcnt lgkmcnt(8)
; #define LAS __attribute__((address_space(3)))
; template <int SRC, int EXTRA, bool OUT8 = false> ...
;     ...
;             for (int e = 0; e < 8; ++e) { float a = 0.f;
; #pragma unroll
;                 for (int j = 0; j < 4; ++j) { const f32x4 w = *(const LAS f32x4*)(w8s + e * 1024 + 256 * j + 4 * lane); a += (v[j].x * w.x + v[j].y * w.y) + (v[j].z * w.z + v[j].w * w.w); }
;                 d[e] = wave_sum(a); }
;             if (EXTRA == 1) {
;                 float x = d[0];
; #pragma unroll
;                 for (int e = 1; e < 8; ++e) x = (lane == e) ? d[e] : x;
;                 if (lane < 8) { x += bf8[lane]; const float ls = (x >= 0.f) ? -log1pf(__expf(-x)) : (x - log1pf(__expf(x))); logf[(size_t)lane * M + row] = ls; }
	v_pk_fma_f32 v[104:105], v[44:45], v[128:129], v[104:105]
	v_pk_fma_f32 v[106:107], v[44:45], v[144:145], v[106:107]
	v_pk_fma_f32 v[108:109], v[44:45], v[160:161], v[108:109]
	v_pk_fma_f32 v[110:111], v[44:45], v[176:177], v[110:111]
	v_pk_fma_f32 v[104:105], v[42:43], v[130:131], v[104:105]
	v_pk_fma_f32 v[106:107], v[42:43], v[146:147], v[106:107]
	v_pk_fma_f32 v[108:109], v[42:43], v[162:163], v[108:109]
	v_pk_fma_f32 v[110:111], v[42:43], v[178:179], v[110:111]
	s_waitcnt lgkmcnt(4)
	v_pk_fma_f32 v[104:105], v[46:47], v[132:133], v[104:105]
	v_pk_fma_f32 v[106:107], v[46:47], v[148:149], v[106:107]
	v_pk_fma_f32 v[108:109], v[46:47], v[164:165], v[108:109]
	v_pk_fma_f32 v[110:111], v[46:47], v[180:181], v[110:111]
	v_pk_fma_f32 v[104:105], v[38:39], v[134:135], v[104:105]
	v_pk_fma_f32 v[106:107], v[38:39], v[150:151], v[106:107]
	v_pk_fma_f32 v[108:109], v[38:39], v[166:167], v[108:109]
	v_pk_fma_f32 v[110:111], v[38:39], v[182:183], v[110:111]
	s_waitcnt lgkmcnt(0)
	v_pk_fma_f32 v[104:105], v[48:49], v[136:137], v[104:105]
	v_pk_fma_f32 v[106:107], v[48:49], v[152:153], v[106:107]
	v_pk_fma_f32 v[108:109], v[48:49], v[168:169], v[108:109]
	v_pk_fma_f32 v[110:111], v[48:49], v[184:185], v[110:111]
	v_pk_fma_f32 v[104:105], v[34:35], v[138:139], v[104:105]
	v_pk_fma_f32 v[106:107], v[34:35], v[154:155], v[106:107]
	v_pk_fma_f32 v[108:109], v[34:35], v[170:171], v[108:109]
	v_pk_fma_f32 v[110:111], v[34:35], v[186:187], v[110:111]
	v_add_f32_e32 v100, v104, v105
	v_add_f32_e32 v101, v106, v107
	v_add_f32_e32 v102, v108, v109
	v_add_f32_e32 v103, v110, v111
	s_nop 0
	v_add_f32_dpp v104, v96, v96 quad_perm:[1,0,3,2] row_mask:0xf bank_mask:0xf
	v_add_f32_dpp v105, v97, v97 quad_perm:[1,0,3,2] row_mask:0xf bank_mask:0xf
	v_cndmask_b32_e64 v112, v104, v105, s[58:59]
	v_add_f32_dpp v106, v98, v98 quad_perm:[1,0,3,2] row_mask:0xf bank_mask:0xf
	v_add_f32_dpp v107, v99, v99 quad_perm:[1,0,3,2] row_mask:0xf bank_mask:0xf
	v_cndmask_b32_e64 v113, v106, v107, s[58:59]
	v_add_f32_dpp v108, v100, v100 quad_perm:[1,0,3,2] row_mask:0xf bank_mask:0xf
	v_add_f32_dpp v109, v101, v101 quad_perm:[1,0,3,2] row_mask:0xf bank_mask:0xf
	v_cndmask_b32_e64 v114, v108, v109, s[58:59]
	v_add_f32_dpp v110, v102, v102 quad_perm:[1,0,3,2] row_mask:0xf bank_mask:0xf
	v_add_f32_dpp v111, v103, v103 quad_perm:[1,0,3,2] row_mask:0xf bank_mask:0xf
	v_cndmask_b32_e64 v115, v110, v111, s[58:59]
	v_add_f32_dpp v104, v112, v112 quad_perm:[2,3,0,1] row_mask:0xf bank_mask:0xf
	v_add_f32_dpp v105, v113, v113 quad_perm:[2,3,0,1] row_mask:0xf bank_mask:0xf
	v_cndmask_b32_e64 v116, v104, v105, s[60:61]
	v_add_f32_dpp v106, v114, v114 quad_perm:[2,3,0,1] row_mask:0xf bank_mask:0xf
	v_add_f32_dpp v107, v115, v115 quad_perm:[2,3,0,1] row_mask:0xf bank_mask:0xf
	v_cndmask_b32_e64 v117, v106, v107, s[60:61]
	v_add_f32_dpp v104, v116, v116 row_shl:4 row_mask:0xf bank_mask:0x5
	v_add_f32_dpp v104, v116, v116 row_shr:4 row_mask:0xf bank_mask:0xa
	v_add_f32_dpp v105, v117, v117 row_shl:4 row_mask:0xf bank_mask:0x5
	v_add_f32_dpp v105, v117, v117 row_shr:4 row_mask:0xf bank_mask:0xa
	v_cndmask_b32_e64 v118, v104, v105, s[62:63]
	s_nop 1
	v_add_f32_dpp v119, v118, v118 row_ror:8 row_mask:0xf bank_mask:0xf
	v_mov_b32_e32 v104, v119
	v_mov_b32_e32 v120, v119
	s_nop 1
	v_permlane16_swap_b32_e32 v104, v120
	v_cndmask_b32_e64 v104, v120, v104, s[98:99]
	v_add_f32_e32 v119, v119, v104
	v_mov_b32_e32 v104, v119
	v_mov_b32_e32 v120, v119
	s_nop 1
	v_permlane32_swap_b32_e32 v104, v120
	v_cndmask_b32_e64 v104, v120, v104, s[100:101]
	v_add_f32_e32 v34, v119, v104
	s_and_saveexec_b64 s[22:23], s[6:7]
	s_cbranch_execz .LBB0_58
	v_add_f32_e32 v34, v34, v206
	v_cmp_le_f32_e32 vcc, 0, v34
	s_and_saveexec_b64 s[42:43], vcc
	s_xor_b64 s[42:43], exec, s[42:43]
	s_cbranch_execz .LBB0_64
; template <int SRC, int EXTRA, bool OUT8 = false> ...
;     ...
;             if (EXTRA == 1) {
;                 float x = d[0];
; #pragma unroll
;                 for (int e = 1; e < 8; ++e) x = (lane == e) ? d[e] : x;
;                 if (lane < 8) { x += bf8[lane]; const float ls = (x >= 0.f) ? -log1pf(__expf(-x)) : (x - log1pf(__expf(x))); logf[(size_t)lane * M + row] = ls; }
	v_mul_f32_e32 v34, 0xbfb8aa3b, v34
	v_exp_f32_e32 v48, v34
	s_nop 0
	v_add_f32_e32 v36, 1.0, v48
	v_frexp_mant_f32_e32 v38, v36
	v_cvt_f64_f32_e32 v[34:35], v36
	v_frexp_exp_i32_f64_e32 v34, v[34:35]
	v_cmp_gt_f32_e32 vcc, s47, v38
	v_add_f32_e32 v37, -1.0, v36
	v_sub_f32_e32 v39, v37, v36
	v_subbrev_co_u32_e32 v42, vcc, 0, v34, vcc
	v_sub_u32_e32 v34, 0, v42
	v_sub_f32_e32 v37, v48, v37
	v_add_f32_e32 v39, 1.0, v39
	v_ldexp_f32 v35, v36, v34
	v_add_f32_e32 v37, v37, v39
	v_add_f32_e32 v36, -1.0, v35
	v_add_f32_e32 v38, 1.0, v35
	v_ldexp_f32 v34, v37, v34
	v_add_f32_e32 v37, 1.0, v36
	v_add_f32_e32 v39, -1.0, v38
	v_sub_f32_e32 v37, v35, v37
	v_sub_f32_e32 v35, v35, v39
	v_add_f32_e32 v37, v34, v37
	v_add_f32_e32 v34, v34, v35
	v_add_f32_e32 v43, v38, v34
	v_rcp_f32_e32 v45, v43
	v_sub_f32_e32 v35, v43, v38
	v_sub_f32_e32 v44, v34, v35
	v_add_f32_e32 v35, v36, v37
	v_mul_f32_e32 v47, v35, v45
	v_sub_f32_e32 v34, v35, v36
	v_mul_f32_e32 v36, v43, v47
	v_fma_f32 v38, v47, v43, -v36
	v_fmac_f32_e32 v38, v47, v44
	v_sub_f32_e32 v46, v37, v34
	v_add_f32_e32 v34, v36, v38
	v_sub_f32_e32 v37, v35, v34
	v_pk_add_f32 v[40:41], v[34:35], v[36:37] neg_lo:[0,1] neg_hi:[0,1]
	v_mov_b32_e32 v39, v34
	v_pk_add_f32 v[34:35], v[40:41], v[38:39] neg_lo:[0,1] neg_hi:[0,1]
	v_cmp_neq_f32_e32 vcc, s49, v48
	v_add_f32_e32 v35, v46, v35
	v_add_f32_e32 v34, v34, v35
	v_add_f32_e32 v35, v37, v34
	v_mul_f32_e32 v46, v45, v35
	v_mul_f32_e32 v36, v43, v46
	v_fma_f32 v38, v46, v43, -v36
	v_fmac_f32_e32 v38, v46, v44
	v_sub_f32_e32 v37, v37, v35
	v_add_f32_e32 v43, v34, v37
	v_add_f32_e32 v34, v36, v38
	v_sub_f32_e32 v37, v35, v34
	v_pk_add_f32 v[40:41], v[34:35], v[36:37] neg_lo:[0,1] neg_hi:[0,1]
	v_mov_b32_e32 v39, v34
	v_pk_add_f32 v[34:35], v[40:41], v[38:39] neg_lo:[0,1] neg_hi:[0,1]
	s_nop 0
	v_add_f32_e32 v35, v43, v35
	v_add_f32_e32 v34, v34, v35
	v_add_f32_e32 v35, v47, v46
	v_add_f32_e32 v34, v37, v34
	v_sub_f32_e32 v36, v35, v47
	v_mul_f32_e32 v34, v45, v34
	v_sub_f32_e32 v36, v46, v36
	v_add_f32_e32 v36, v36, v34
	v_add_f32_e32 v38, v35, v36
	v_mul_f32_e32 v39, v38, v38
	v_fmamk_f32 v34, v39, 0x3e9b6dac, v69
	v_fmaak_f32 v63, v39, v34, 0x3f2aaada
	v_cvt_f32_i32_e32 v34, v42
	v_sub_f32_e32 v35, v38, v35
	v_sub_f32_e32 v35, v36, v35
	v_ldexp_f32 v40, v35, 1
	v_mul_f32_e32 v35, v38, v39
	v_ldexp_f32 v37, v38, 1
	v_pk_mul_f32 v[38:39], v[34:35], v[62:63]
	s_nop 0
	v_fma_f32 v36, v34, s48, -v38
	v_fmac_f32_e32 v36, 0xb102e308, v34
	v_pk_add_f32 v[34:35], v[38:39], v[36:37]
	s_nop 0
	v_sub_f32_e32 v37, v35, v37
	v_sub_f32_e32 v37, v39, v37
	v_add_f32_e32 v41, v40, v37
	v_mov_b32_e32 v40, v38
	v_pk_add_f32 v[38:39], v[34:35], v[38:39] neg_lo:[0,1] neg_hi:[0,1]
	v_pk_add_f32 v[42:43], v[34:35], v[40:41]
	v_mov_b32_e32 v37, v34
	v_mov_b32_e32 v39, v43
	v_pk_add_f32 v[44:45], v[36:37], v[38:39] neg_lo:[0,1] neg_hi:[0,1]
	v_pk_add_f32 v[36:37], v[36:37], v[38:39]
	v_mov_b32_e32 v40, v41
	v_pk_add_f32 v[38:39], v[36:37], v[34:35] op_sel:[1,0] op_sel_hi:[0,1] neg_lo:[0,1] neg_hi:[0,1]
	v_pk_add_f32 v[46:47], v[42:43], v[38:39] op_sel_hi:[1,0] neg_lo:[0,1] neg_hi:[0,1]
	v_mov_b32_e32 v42, v43
	v_mov_b32_e32 v43, v37
	v_pk_mov_b32 v[38:39], v[34:35], v[38:39] op_sel:[1,0]
	v_mov_b32_e32 v41, v34
	v_pk_add_f32 v[38:39], v[42:43], v[38:39] neg_lo:[0,1] neg_hi:[0,1]
	v_mov_b32_e32 v46, v44
	v_pk_add_f32 v[34:35], v[40:41], v[38:39] neg_lo:[0,1] neg_hi:[0,1]
	v_mov_b32_e32 v45, v37
	v_pk_add_f32 v[38:39], v[46:47], v[34:35]
	s_nop 0
	v_pk_add_f32 v[40:41], v[38:39], v[38:39] op_sel:[0,1] op_sel_hi:[1,0]
	s_nop 0
	v_pk_add_f32 v[36:37], v[36:37], v[40:41] op_sel:[1,0] op_sel_hi:[0,1]
	v_mov_b32_e32 v39, v36
	v_pk_add_f32 v[42:43], v[38:39], v[44:45] neg_lo:[0,1] neg_hi:[0,1]
	v_mov_b32_e32 v35, v40
	v_sub_f32_e32 v37, v38, v42
	v_pk_add_f32 v[34:35], v[34:35], v[42:43] neg_lo:[0,1] neg_hi:[0,1]
	v_sub_f32_e32 v37, v44, v37
	v_add_f32_e32 v34, v34, v37
	v_add_f32_e32 v34, v34, v35
	v_add_f32_e32 v34, v36, v34
	v_cndmask_b32_e32 v34, v70, v34, vcc
	v_cmp_ngt_f32_e32 vcc, -1.0, v48
	s_nop 1
	v_cndmask_b32_e32 v34, v71, v34, vcc
	v_cmp_neq_f32_e32 vcc, -1.0, v48
	s_nop 1
	v_cndmask_b32_e32 v34, v72, v34, vcc
	v_cmp_lt_f32_e64 vcc, |v48|, s50
	s_nop 1
	v_cndmask_b32_e32 v34, v34, v48, vcc
	v_xor_b32_e32 v35, 0x80000000, v34

; __device__ __forceinline__ int mk_tid(int wv) { return (wv << 6) | lane_now(); }
; #define LAS __attribute__((address_space(3)))
; template <int SRC, int EXTRA, bool OUT8 = false> ...
;     const int tid = mk_tid(wv); const int lane = tid & 63, wave = wv;
;     LAS float* w8s = (LAS float*)lds;
;     LAS unsigned* lcnt = (LAS unsigned*)(lds + 32768);
;     if (EXTRA != 0) { for (int i = tid; i < 8192; i += NT) { const int k = i >> 3, j = i & 7; w8s[j * 1024 + k] = w8[(size_t)k * w8ld + j]; } if (tid < 8) lcnt[tid] = 0u; __syncthreads(); }
;     f32x4 gv[4], bv[4];
; #pragma unroll
;     for (int j = 0; j < 4; ++j) { gv[j] = *(const f32x4*)(g + 256 * j + 4 * lane); bv[j] = *(const f32x4*)(b + 256 * j + 4 * lane); }
;     const int gw = blockIdx.x * NWAVES + wave, NGW = G * NWAVES;
;     for (int row = gw; row < M; row += NGW) {
.LBB0_837:
	s_or_b64 exec, exec, s[4:5]
	s_waitcnt lgkmcnt(0)
	v_cndmask_b32_e64 v0, 0, 1, s[38:39]
	s_mov_b64 s[10:11], s[0:1]
	s_mov_b64 s[16:17], s[0:1]
	s_mov_b64 s[18:19], s[0:1]
	s_mov_b64 s[14:15], s[0:1]
	s_mov_b64 s[12:13], s[0:1]
	v_cmp_ne_u32_e64 s[4:5], 1, v0
	s_andn2_b64 vcc, exec, s[38:39]
	s_barrier
	v_mbcnt_lo_u32_b32 v0, -1, 0
	v_mbcnt_hi_u32_b32 v0, -1, v0
	s_cbranch_vccnz .LBB0_842
	s_load_dwordx2 s[20:21], s[16:17], 0x68
	s_load_dwordx2 s[22:23], s[18:19], 0x70
	v_and_b32_e32 v33, 63, v0
	v_lshlrev_b32_e32 v32, 4, v33
	v_lshlrev_b32_e32 v48, 2, v33
	v_mov_b32_e32 v49, 0
	s_waitcnt lgkmcnt(0)
	global_load_dwordx4 v[0:3], v32, s[20:21]
	global_load_dwordx4 v[4:7], v32, s[20:21] offset:1024
	global_load_dwordx4 v[8:11], v32, s[22:23]
	global_load_dwordx4 v[12:15], v32, s[22:23] offset:1024
	global_load_dwordx4 v[16:19], v32, s[20:21] offset:2048
	global_load_dwordx4 v[20:23], v32, s[20:21] offset:3072
	global_load_dwordx4 v[24:27], v32, s[22:23] offset:2048
	global_load_dwordx4 v[28:31], v32, s[22:23] offset:3072
	s_load_dwordx2 s[16:17], s[14:15], 0xc0
	s_load_dwordx2 s[18:19], s[10:11], 0xc0
	v_cmp_eq_u32_e64 s[10:11], 0, v33
	s_load_dwordx2 s[12:13], s[12:13], 0xc0
	v_mov_b32_e32 v33, v49
	s_waitcnt lgkmcnt(0)
	s_add_u32 s3, s16, 0x400000
	s_addc_u32 s20, s17, 0
	s_lshl_b32 s14, s2, 4
	s_lshl_b32 s15, s68, 1
	s_ashr_i32 s35, s34, 31
	s_add_i32 s14, s14, s15
	s_lshl_b32 s21, s33, 4
	s_lshl_b64 s[16:17], s[34:35], 10
	s_add_u32 s12, s12, s16
	s_addc_u32 s13, s13, s17
	v_lshl_add_u64 v[34:35], s[12:13], 0, v[48:49]
	s_mov_b64 s[12:13], 0x12500300
	s_ashr_i32 s31, s30, 31
	v_lshl_add_u64 v[50:51], v[34:35], 0, s[12:13]
	s_lshl_b64 s[16:17], s[30:31], 10
	s_lshl_b64 s[12:13], s[34:35], 12
	s_add_u32 s12, s18, s12
	s_addc_u32 s13, s19, s13
	v_lshl_add_u64 v[32:33], s[12:13], 0, v[32:33]
	s_mov_b64 s[12:13], 0x28500c00
	v_lshl_add_u64 v[52:53], v[32:33], 0, s[12:13]
	s_lshl_b64 s[18:19], s[30:31], 12
	v_mov_b32_e32 v54, 0x3727c5ac
	s_mov_b32 s22, 0xf800000
	v_mov_b32_e32 v55, 0x260
	s_mov_b32 s23, s34
	global_load_dwordx4 v[200:203], v[52:53], off offset:-3072
	global_load_dwordx4 v[196:199], v[52:53], off offset:-2048
	global_load_dwordx4 v[192:195], v[52:53], off offset:-1024
	global_load_dwordx4 v[188:191], v[52:53], off
	s_waitcnt vmcnt(0)
	s_branch .LBB0_840

; template <int SRC, int EXTRA, bool OUT8 = false> ...
;     ...
;     for (int row = gw; row < M; row += NGW) {
;         f32x4 v[4];
;         if (SRC == 0) {
; #pragma unroll
;             for (int j = 0; j < 4; ++j) v[j] = *(const f32x4*)(src + (size_t)row * 1024 + 256 * j + 4 * lane);
;         } else {
;             const int p0 = pos[2 * row], p1 = pos[2 * row + 1]; const float w0 = gwt[2 * row], w1 = gwt[2 * row + 1]; const float hm = hp.stats[2 * row], hr = hp.stats[2 * row + 1];
; #pragma unroll
;             for (int j = 0; j < 4; ++j) { const f32x4 a = (*(const f32x4*)(hp.src + (size_t)row * 1024 + 256 * j + 4 * lane) - hm) * hr * *(const f32x4*)(hp.g + 256 * j + 4 * lane) + *(const f32x4*)(hp.b + 256 * j + 4 * lane);
;                 f32x4 y[2];
; #pragma unroll
;                 for (int q = 0; q < 2; ++q) { const int p = q ? p1 : p0; const int t = __builtin_amdgcn_readfirstlane(tailid[(p >> 8) * 4 + j]);
;                     if (t < 0) y[q] = *(const f32x4*)(ys + (size_t)p * 1024 + 256 * j + 4 * lane);
;                     else { f32x4 acc = (f32x4){0.f, 0.f, 0.f, 0.f};
; #pragma unroll
;                         for (int sl = 0; sl < 7; ++sl) acc = acc + *(const f32x4*)(part + ((size_t)(t * 7 + sl) * 256 + (p & 255)) * 256 + 4 * lane);
;                         y[q] = acc; } }
;                 v[j] = a * ALPHA + y[0] * w0 + y[1] * w1; }
;         }
;         float s = 0.f;
; #pragma unroll
;         for (int j = 0; j < 4; ++j) s += (v[j].x + v[j].y) + (v[j].z + v[j].w);
;         const float mean = wave_sum(s) * (1.f / 1024.f); float s2 = 0.f;
; #pragma unroll
;         for (int j = 0; j < 4; ++j) { v[j] = v[j] - mean; s2 += (v[j].x * v[j].x + v[j].y * v[j].y) + (v[j].z * v[j].z + v[j].w * v[j].w); }
;         const float rstd = 1.f / sqrtf(wave_sum(s2) * (1.f / 1024.f) + LN_EPS);
;         if (stats && lane == 0) { stats[2 * row] = mean; stats[2 * row + 1] = rstd; }
.LBB0_840:
	s_waitcnt vmcnt(4)
	v_mov_b64_e32 v[32:33], v[188:189]
	v_mov_b64_e32 v[34:35], v[190:191]
	v_mov_b64_e32 v[36:37], v[192:193]
	v_mov_b64_e32 v[38:39], v[194:195]
	v_mov_b64_e32 v[40:41], v[196:197]
	v_mov_b64_e32 v[42:43], v[198:199]
	v_mov_b64_e32 v[44:45], v[200:201]
	v_mov_b64_e32 v[46:47], v[202:203]
	s_add_i32 s95, s23, s30
	s_cmpk_lt_i32 s95, 0x4000
	s_cbranch_scc0 .Lrowpf_22491
	v_lshl_add_u64 v[204:205], v[52:53], 0, s[18:19]
	global_load_dwordx4 v[200:203], v[204:205], off offset:-3072
	global_load_dwordx4 v[196:199], v[204:205], off offset:-2048
	global_load_dwordx4 v[192:195], v[204:205], off offset:-1024
	global_load_dwordx4 v[188:191], v[204:205], off
.Lrowpf_22491:
	s_waitcnt lgkmcnt(0)
	v_mov_b32_e32 v56, v45
	v_mov_b32_e32 v57, v46
	v_mov_b32_e32 v58, v44
	v_mov_b32_e32 v59, v47
	v_mov_b32_e32 v60, v41
	v_mov_b32_e32 v61, v42
	v_mov_b32_e32 v62, v40
	v_mov_b32_e32 v63, v43
	v_pk_add_f32 v[56:57], v[56:57], v[58:59]
	v_pk_add_f32 v[58:59], v[60:61], v[62:63]
	v_add_f32_e32 v62, v56, v57
	v_pk_add_f32 v[56:57], v[58:59], v[58:59] op_sel:[0,1] op_sel_hi:[1,0]
	v_add_f32_e32 v64, v36, v37
	v_add_f32_e32 v66, v38, v39
	v_mov_b32_e32 v69, v32
	v_mov_b32_e32 v65, v34
	v_mov_b32_e32 v67, v35
	v_add_f32_e32 v68, 0, v62
	v_mov_b32_e32 v57, v33
	v_pk_add_f32 v[60:61], v[64:65], v[66:67]
	v_pk_add_f32 v[56:57], v[68:69], v[56:57]
	v_pk_add_f32 v[56:57], v[56:57], v[60:61]
	v_add_f32_e32 v56, v56, v57
	s_nop 1
	v_mov_b32_dpp v48, v56 quad_perm:[1,0,3,2] row_mask:0xf bank_mask:0xf
	v_add_f32_e32 v48, v56, v48
	s_nop 1
	v_mov_b32_dpp v56, v48 quad_perm:[2,3,0,1] row_mask:0xf bank_mask:0xf
	v_add_f32_e32 v48, v48, v56
	s_nop 1
	v_mov_b32_dpp v56, v48 row_shl:4 row_mask:0xf bank_mask:0x5
	v_mov_b32_dpp v56, v48 row_shr:4 row_mask:0xf bank_mask:0xa
	v_add_f32_e32 v48, v48, v56
	s_nop 1
	v_mov_b32_dpp v56, v48 row_ror:8 row_mask:0xf bank_mask:0xf
	v_add_f32_e32 v48, v48, v56
	v_mov_b32_e32 v56, v48
	v_mov_b32_e32 v120, v48
	s_nop 1
	v_permlane16_swap_b32_e32 v56, v120
	v_cndmask_b32_e64 v56, v120, v56, s[98:99]
	v_add_f32_e32 v48, v48, v56
	v_mov_b32_e32 v56, v48
	v_mov_b32_e32 v120, v48
	s_nop 1
	v_permlane32_swap_b32_e32 v56, v120
	v_cndmask_b32_e64 v56, v120, v56, s[100:101]
	v_add_f32_e32 v56, v48, v56
	v_fmamk_f32 v47, v56, 0xba800000, v47
	v_fmamk_f32 v45, v56, 0xba800000, v45
	v_fmamk_f32 v43, v56, 0xba800000, v43
	v_fmamk_f32 v41, v56, 0xba800000, v41
	v_fmamk_f32 v46, v56, 0xba800000, v46
	v_fmac_f32_e32 v44, 0xba800000, v56
	v_fmamk_f32 v42, v56, 0xba800000, v42
	v_fmac_f32_e32 v40, 0xba800000, v56
	v_fmamk_f32 v39, v56, 0xba800000, v39
	v_fmamk_f32 v37, v56, 0xba800000, v37
	v_mul_f32_e32 v48, v45, v45
	v_mul_f32_e32 v58, v47, v47
	v_mul_f32_e32 v59, v41, v41
	v_mul_f32_e32 v60, v43, v43
	v_fmamk_f32 v38, v56, 0xba800000, v38
	v_fmac_f32_e32 v36, 0xba800000, v56
	v_fmamk_f32 v35, v56, 0xba800000, v35
	v_fmamk_f32 v33, v56, 0xba800000, v33
	v_mul_f32_e32 v61, v37, v37
	v_mul_f32_e32 v62, v39, v39
	v_fmac_f32_e32 v48, v44, v44
	v_fmac_f32_e32 v58, v46, v46
	v_fmac_f32_e32 v59, v40, v40
	v_fmac_f32_e32 v60, v42, v42
	v_fmamk_f32 v34, v56, 0xba800000, v34
	v_fmac_f32_e32 v32, 0xba800000, v56
	v_mul_f32_e32 v63, v33, v33
	v_mul_f32_e32 v64, v35, v35
	v_fmac_f32_e32 v61, v36, v36
	v_fmac_f32_e32 v62, v38, v38
	v_add_f32_e32 v48, v48, v58
	v_add_f32_e32 v58, v59, v60
	v_fmac_f32_e32 v63, v32, v32
	v_fmac_f32_e32 v64, v34, v34
	v_add_f32_e32 v59, v61, v62
	v_add_f32_e32 v48, v48, v58
	v_add_f32_e32 v60, v63, v64
	v_add_f32_e32 v48, v59, v48
	v_add_f32_e32 v48, v60, v48
	s_nop 1
	v_mov_b32_dpp v57, v48 quad_perm:[1,0,3,2] row_mask:0xf bank_mask:0xf
	v_add_f32_e32 v48, v48, v57
	s_nop 1
	v_mov_b32_dpp v57, v48 quad_perm:[2,3,0,1] row_mask:0xf bank_mask:0xf
	v_add_f32_e32 v48, v48, v57
	s_nop 1
	v_mov_b32_dpp v57, v48 row_shl:4 row_mask:0xf bank_mask:0x5
	v_mov_b32_dpp v57, v48 row_shr:4 row_mask:0xf bank_mask:0xa
	v_add_f32_e32 v48, v48, v57
	s_nop 1
	v_mov_b32_dpp v57, v48 row_ror:8 row_mask:0xf bank_mask:0xf
	v_add_f32_e32 v48, v48, v57
	v_mov_b32_e32 v57, v48
	v_mov_b32_e32 v120, v48
	s_nop 1
	v_permlane16_swap_b32_e32 v57, v120
	v_cndmask_b32_e64 v57, v120, v57, s[98:99]
	v_add_f32_e32 v48, v48, v57
	v_mov_b32_e32 v57, v48
	v_mov_b32_e32 v120, v48
	s_nop 1
	v_permlane32_swap_b32_e32 v57, v120
	v_cndmask_b32_e64 v57, v120, v57, s[100:101]
	v_add_f32_e32 v48, v48, v57
	v_fmamk_f32 v48, v48, 0x3a800000, v54
	v_mul_f32_e32 v57, 0x4f800000, v48
	v_cmp_gt_f32_e32 vcc, s22, v48
	s_nop 1
	v_cndmask_b32_e32 v48, v48, v57, vcc
	v_sqrt_f32_e32 v57, v48
	s_nop 0
	v_add_u32_e32 v58, -1, v57
	v_add_u32_e32 v59, 1, v57
	v_fma_f32 v60, -v58, v57, v48
	v_fma_f32 v61, -v59, v57, v48
	v_cmp_ge_f32_e64 s[12:13], 0, v60
	s_nop 1
	v_cndmask_b32_e64 v57, v57, v58, s[12:13]
	v_cmp_lt_f32_e64 s[12:13], 0, v61
	s_nop 1
	v_cndmask_b32_e64 v57, v57, v59, s[12:13]
	v_mul_f32_e32 v58, 0x37800000, v57
	v_cndmask_b32_e32 v57, v57, v58, vcc
	v_cmp_class_f32_e32 vcc, v48, v55
	s_nop 1
	v_cndmask_b32_e32 v48, v57, v48, vcc
	v_div_scale_f32 v57, s[12:13], v48, v48, 1.0
	v_rcp_f32_e32 v58, v57
	v_div_scale_f32 v59, vcc, 1.0, v48, 1.0
	v_fma_f32 v60, -v57, v58, 1.0
	v_fmac_f32_e32 v58, v60, v58
	v_mul_f32_e32 v60, v59, v58
	v_fma_f32 v61, -v57, v60, v59
	v_fmac_f32_e32 v60, v61, v58
	v_fma_f32 v57, -v57, v60, v59
	v_div_fmas_f32 v57, v57, v58, v60
	v_div_fixup_f32 v48, v57, v48, 1.0
	s_and_saveexec_b64 s[12:13], s[10:11]
	s_cbranch_execz .LBB0_839
	s_ashr_i32 s15, s14, 31
	s_lshl_b64 s[24:25], s[14:15], 2
	s_add_u32 s24, s3, s24
	v_mul_f32_e32 v56, 0x3a800000, v56
	s_addc_u32 s25, s20, s25
	v_mov_b32_e32 v57, v48
	global_store_dwordx2 v49, v[56:57], s[24:25]
	s_branch .LBB0_839

; __device__ __forceinline__ int mk_tid(int wv) { return (wv << 6) | lane_now(); }
; #define LAS __attribute__((address_space(3)))
; template <int SRC, int EXTRA, bool OUT8 = false> ...
;     const int tid = mk_tid(wv); const int lane = tid & 63, wave = wv;
;     LAS float* w8s = (LAS float*)lds;
;     LAS unsigned* lcnt = (LAS unsigned*)(lds + 32768);
;     if (EXTRA != 0) { for (int i = tid; i < 8192; i += NT) { const int k = i >> 3, j = i & 7; w8s[j * 1024 + k] = w8[(size_t)k * w8ld + j]; } if (tid < 8) lcnt[tid] = 0u; __syncthreads(); }
;     f32x4 gv[4], bv[4];
; #pragma unroll
;     for (int j = 0; j < 4; ++j) { gv[j] = *(const f32x4*)(g + 256 * j + 4 * lane); bv[j] = *(const f32x4*)(b + 256 * j + 4 * lane); }
;     const int gw = blockIdx.x * NWAVES + wave, NGW = G * NWAVES;
;     for (int row = gw; row < M; row += NGW) {
.LBB0_1051:
	s_or_b64 exec, exec, s[18:19]
	v_cmp_gt_i32_e32 vcc, 8, v0
	s_and_saveexec_b64 s[18:19], vcc
	v_lshl_add_u32 v0, v0, 2, 0
	v_mov_b32_e32 v1, 0
	ds_write_b32 v0, v1 offset:32768
	s_or_b64 exec, exec, s[18:19]
	s_and_b64 vcc, exec, s[4:5]
	s_waitcnt lgkmcnt(0)
	s_barrier
	s_cbranch_vccnz .LBB0_1064
	v_and_b32_e32 v34, 63, v6
	v_lshlrev_b32_e32 v48, 4, v34
	global_load_dwordx4 v[0:3], v48, s[10:11]
	global_load_dwordx4 v[4:7], v48, s[10:11] offset:1024
	global_load_dwordx4 v[8:11], v48, s[14:15]
	global_load_dwordx4 v[12:15], v48, s[14:15] offset:1024
	global_load_dwordx4 v[16:19], v48, s[10:11] offset:2048
	global_load_dwordx4 v[20:23], v48, s[10:11] offset:3072
	global_load_dwordx4 v[24:27], v48, s[14:15] offset:2048
	global_load_dwordx4 v[28:31], v48, s[14:15] offset:3072
	s_add_u32 s3, s12, 0x400000
	s_addc_u32 s40, s13, 0
	s_lshl_b32 s31, s2, 4
	s_lshl_b32 s35, s68, 1
	s_add_i32 s44, s31, s35
	s_ashr_i32 s35, s34, 31
	s_lshl_b32 s41, s33, 4
	s_lshl_b64 s[42:43], s[34:35], 2
	v_lshlrev_b32_e32 v50, 2, v34
	v_mov_b32_e32 v51, 0
	s_add_u32 s42, s46, s42
	v_lshl_add_u64 v[52:53], s[16:17], 0, v[50:51]
	v_lshlrev_b32_e32 v50, 16, v34
	s_addc_u32 s43, s47, s43
	v_lshl_add_u64 v[32:33], s[42:43], 0, v[50:51]
	s_mov_b64 s[42:43], 0x100000
	s_ashr_i32 s31, s30, 31
	v_lshl_add_u64 v[54:55], v[32:33], 0, s[42:43]
	s_lshl_b64 s[46:47], s[30:31], 2
	s_lshl_b64 s[42:43], s[34:35], 11
	s_add_u32 s42, s48, s42
	v_lshlrev_b32_e32 v50, 3, v34
	s_addc_u32 s43, s49, s43
	v_lshl_add_u64 v[32:33], s[42:43], 0, v[50:51]
	s_mov_b64 s[42:43], 0x12500600
	v_lshl_add_u64 v[56:57], v[32:33], 0, s[42:43]
	s_lshl_b64 s[48:49], s[30:31], 11
	s_lshl_b64 s[42:43], s[34:35], 12
	s_add_u32 s28, s28, s42
	v_mov_b32_e32 v49, v51
	s_addc_u32 s29, s29, s43
	v_lshl_add_u64 v[32:33], s[28:29], 0, v[48:49]
	s_mov_b64 s[28:29], 0x28500c00
	v_cmp_eq_u32_e64 s[10:11], 0, v34
	v_cmp_gt_u32_e64 s[12:13], 8, v34
	v_cmp_eq_u32_e64 s[14:15], 7, v34
	v_cmp_eq_u32_e64 s[16:17], 6, v34
	v_cmp_eq_u32_e64 s[18:19], 5, v34
	v_cmp_eq_u32_e64 s[20:21], 4, v34
	v_cmp_eq_u32_e64 s[22:23], 3, v34
	v_cmp_eq_u32_e64 s[24:25], 2, v34
	v_cmp_eq_u32_e64 s[26:27], 1, v34
	v_lshl_add_u64 v[58:59], v[32:33], 0, s[28:29]
	s_lshl_b64 s[50:51], s[30:31], 12
	v_mov_b32_e32 v49, 0x3727c5ac
	s_mov_b32 s31, 0xf800000
	v_mov_b32_e32 v66, 0x260
	s_movk_i32 s35, 0x7fff
	s_mov_b32 s42, 0xffff0000
	s_mov_b32 s43, 0x3f2aaaab
	v_mov_b32_e32 v67, 0x3ecc95a3
	s_mov_b32 s54, 0x3f317218
	s_mov_b32 s55, 0x7f800000
	s_mov_b32 s56, 0x33800000
	v_mov_b32_e32 v60, 0x3f317218
	v_mov_b32_e32 v68, 0x7f800000
	v_mov_b32_e32 v69, 0x7fc00000
	v_mov_b32_e32 v70, 0xff800000
	s_mov_b32 s57, s34
	global_load_dwordx4 v[200:203], v[58:59], off offset:-3072
	global_load_dwordx4 v[196:199], v[58:59], off offset:-2048
	global_load_dwordx4 v[192:195], v[58:59], off offset:-1024
	global_load_dwordx4 v[188:191], v[58:59], off
	s_waitcnt vmcnt(0)
	s_mov_b32 s58, 0xaaaaaaaa
	s_mov_b32 s59, 0xaaaaaaaa
	s_mov_b32 s60, 0xcccccccc
	s_mov_b32 s61, 0xcccccccc
	s_mov_b32 s62, 0xf0f0f0f0
	s_mov_b32 s63, 0xf0f0f0f0
	v_mov_b32_e32 v206, 0
	s_and_saveexec_b64 s[66:67], s[12:13]
	global_load_dword v206, v[52:53], off offset:32
	s_or_b64 exec, exec, s[66:67]
	s_waitcnt vmcnt(0)
	s_branch .LBB0_1057

; template <int SRC, int EXTRA, bool OUT8 = false> ...
;     ...
;     for (int row = gw; row < M; row += NGW) {
;         f32x4 v[4];
;         if (SRC == 0) {
; #pragma unroll
;             for (int j = 0; j < 4; ++j) v[j] = *(const f32x4*)(src + (size_t)row * 1024 + 256 * j + 4 * lane);
;         } else {
;             const int p0 = pos[2 * row], p1 = pos[2 * row + 1]; const float w0 = gwt[2 * row], w1 = gwt[2 * row + 1]; const float hm = hp.stats[2 * row], hr = hp.stats[2 * row + 1];
; #pragma unroll
;             for (int j = 0; j < 4; ++j) { const f32x4 a = (*(const f32x4*)(hp.src + (size_t)row * 1024 + 256 * j + 4 * lane) - hm) * hr * *(const f32x4*)(hp.g + 256 * j + 4 * lane) + *(const f32x4*)(hp.b + 256 * j + 4 * lane);
;                 f32x4 y[2];
; #pragma unroll
;                 for (int q = 0; q < 2; ++q) { const int p = q ? p1 : p0; const int t = __builtin_amdgcn_readfirstlane(tailid[(p >> 8) * 4 + j]);
;                     if (t < 0) y[q] = *(const f32x4*)(ys + (size_t)p * 1024 + 256 * j + 4 * lane);
;                     else { f32x4 acc = (f32x4){0.f, 0.f, 0.f, 0.f};
; #pragma unroll
;                         for (int sl = 0; sl < 7; ++sl) acc = acc + *(const f32x4*)(part + ((size_t)(t * 7 + sl) * 256 + (p & 255)) * 256 + 4 * lane);
;                         y[q] = acc; } }
;                 v[j] = a * ALPHA + y[0] * w0 + y[1] * w1; }
;         }
;         float s = 0.f;
; #pragma unroll
;         for (int j = 0; j < 4; ++j) s += (v[j].x + v[j].y) + (v[j].z + v[j].w);
;         const float mean = wave_sum(s) * (1.f / 1024.f); float s2 = 0.f;
; #pragma unroll
;         for (int j = 0; j < 4; ++j) { v[j] = v[j] - mean; s2 += (v[j].x * v[j].x + v[j].y * v[j].y) + (v[j].z * v[j].z + v[j].w * v[j].w); }
;         const float rstd = 1.f / sqrtf(wave_sum(s2) * (1.f / 1024.f) + LN_EPS);
;         if (stats && lane == 0) { stats[2 * row] = mean; stats[2 * row + 1] = rstd; }
.LBB0_1057:
	s_waitcnt vmcnt(1)
	v_mov_b64_e32 v[32:33], v[188:189]
	v_mov_b64_e32 v[34:35], v[190:191]
	v_mov_b64_e32 v[36:37], v[192:193]
	v_mov_b64_e32 v[38:39], v[194:195]
	v_mov_b64_e32 v[40:41], v[196:197]
	v_mov_b64_e32 v[42:43], v[198:199]
	v_mov_b64_e32 v[44:45], v[200:201]
	v_mov_b64_e32 v[46:47], v[202:203]
	s_add_i32 s95, s57, s30
	s_cmpk_lt_i32 s95, 0x4000
	s_cbranch_scc0 .Lrowpf_27526
	v_lshl_add_u64 v[204:205], v[58:59], 0, s[50:51]
	global_load_dwordx4 v[200:203], v[204:205], off offset:-3072
	global_load_dwordx4 v[196:199], v[204:205], off offset:-2048
	global_load_dwordx4 v[192:195], v[204:205], off offset:-1024
	global_load_dwordx4 v[188:191], v[204:205], off
.Lrowpf_27526:
	s_waitcnt lgkmcnt(0)
	ds_read_b128 v[124:127], v48
	ds_read_b128 v[128:131], v48 offset:1024
	ds_read_b128 v[132:135], v48 offset:2048
	ds_read_b128 v[136:139], v48 offset:3072
	ds_read_b128 v[140:143], v48 offset:4096
	ds_read_b128 v[144:147], v48 offset:5120
	ds_read_b128 v[148:151], v48 offset:6144
	ds_read_b128 v[152:155], v48 offset:7168
	ds_read_b128 v[156:159], v48 offset:8192
	ds_read_b128 v[160:163], v48 offset:9216
	ds_read_b128 v[164:167], v48 offset:10240
	ds_read_b128 v[168:171], v48 offset:11264
	ds_read_b128 v[172:175], v48 offset:12288
	ds_read_b128 v[176:179], v48 offset:13312
	ds_read_b128 v[180:183], v48 offset:14336
	ds_read_b128 v[184:187], v48 offset:15360
	v_mov_b32_e32 v62, v45
	v_mov_b32_e32 v63, v46
	v_mov_b32_e32 v64, v44
	v_mov_b32_e32 v65, v47
	v_mov_b32_e32 v72, v41
	v_mov_b32_e32 v73, v42
	v_mov_b32_e32 v74, v40
	v_mov_b32_e32 v75, v43
	v_pk_add_f32 v[62:63], v[62:63], v[64:65]
	v_pk_add_f32 v[64:65], v[72:73], v[74:75]
	v_add_f32_e32 v61, v62, v63
	v_pk_add_f32 v[62:63], v[64:65], v[64:65] op_sel:[0,1] op_sel_hi:[1,0]
	v_add_f32_e32 v76, v36, v37
	v_add_f32_e32 v78, v38, v39
	v_mov_b32_e32 v81, v32
	v_mov_b32_e32 v77, v34
	v_mov_b32_e32 v79, v35
	v_add_f32_e32 v80, 0, v61
	v_mov_b32_e32 v63, v33
	v_pk_add_f32 v[72:73], v[76:77], v[78:79]
	v_pk_add_f32 v[62:63], v[80:81], v[62:63]
	v_pk_add_f32 v[62:63], v[62:63], v[72:73]
	v_add_f32_e32 v61, v62, v63
	s_nop 1
	v_mov_b32_dpp v50, v61 quad_perm:[1,0,3,2] row_mask:0xf bank_mask:0xf
	v_add_f32_e32 v50, v61, v50
	s_nop 1
	v_mov_b32_dpp v61, v50 quad_perm:[2,3,0,1] row_mask:0xf bank_mask:0xf
	v_add_f32_e32 v50, v50, v61
	s_nop 1
	v_mov_b32_dpp v61, v50 row_shl:4 row_mask:0xf bank_mask:0x5
	v_mov_b32_dpp v61, v50 row_shr:4 row_mask:0xf bank_mask:0xa
	v_add_f32_e32 v50, v50, v61
	s_nop 1
	v_mov_b32_dpp v61, v50 row_ror:8 row_mask:0xf bank_mask:0xf
	v_add_f32_e32 v50, v50, v61
	v_mov_b32_e32 v61, v50
	v_mov_b32_e32 v120, v50
	s_nop 1
	v_permlane16_swap_b32_e32 v61, v120
	v_cndmask_b32_e64 v61, v120, v61, s[98:99]
	v_add_f32_e32 v50, v50, v61
	v_mov_b32_e32 v61, v50
	v_mov_b32_e32 v120, v50
	s_nop 1
	v_permlane32_swap_b32_e32 v61, v120
	v_cndmask_b32_e64 v61, v120, v61, s[100:101]
	v_add_f32_e32 v61, v50, v61
	v_fmamk_f32 v65, v61, 0xba800000, v47
	v_fmamk_f32 v45, v61, 0xba800000, v45
	v_fmamk_f32 v43, v61, 0xba800000, v43
	v_fmamk_f32 v41, v61, 0xba800000, v41
	v_fmamk_f32 v64, v61, 0xba800000, v46
	v_fmac_f32_e32 v44, 0xba800000, v61
	v_fmamk_f32 v42, v61, 0xba800000, v42
	v_fmac_f32_e32 v40, 0xba800000, v61
	v_fmamk_f32 v63, v61, 0xba800000, v39
	v_fmamk_f32 v62, v61, 0xba800000, v38
	v_fmamk_f32 v37, v61, 0xba800000, v37
	v_fmamk_f32 v47, v61, 0xba800000, v35
	v_fmamk_f32 v46, v61, 0xba800000, v34
	v_mul_f32_e32 v34, v45, v45
	v_mul_f32_e32 v35, v65, v65
	v_mul_f32_e32 v38, v41, v41
	v_mul_f32_e32 v39, v43, v43
	v_fmac_f32_e32 v36, 0xba800000, v61
	v_fmamk_f32 v33, v61, 0xba800000, v33
	v_mul_f32_e32 v50, v37, v37
	v_mul_f32_e32 v72, v63, v63
	v_fmac_f32_e32 v34, v44, v44
	v_fmac_f32_e32 v35, v64, v64
	v_fmac_f32_e32 v38, v40, v40
	v_fmac_f32_e32 v39, v42, v42
	v_fmac_f32_e32 v32, 0xba800000, v61
	v_mul_f32_e32 v73, v33, v33
	v_mul_f32_e32 v74, v47, v47
	v_fmac_f32_e32 v50, v36, v36
	v_fmac_f32_e32 v72, v62, v62
	v_add_f32_e32 v34, v34, v35
	v_add_f32_e32 v35, v38, v39
	v_fmac_f32_e32 v73, v32, v32
	v_fmac_f32_e32 v74, v46, v46
	v_add_f32_e32 v38, v50, v72
	v_add_f32_e32 v34, v34, v35
	v_add_f32_e32 v39, v73, v74
	v_add_f32_e32 v34, v38, v34
	v_add_f32_e32 v34, v39, v34
	s_nop 1
	v_mov_b32_dpp v35, v34 quad_perm:[1,0,3,2] row_mask:0xf bank_mask:0xf
	v_add_f32_e32 v34, v34, v35
	s_nop 1
	v_mov_b32_dpp v35, v34 quad_perm:[2,3,0,1] row_mask:0xf bank_mask:0xf
	v_add_f32_e32 v34, v34, v35
	s_nop 1
	v_mov_b32_dpp v35, v34 row_shl:4 row_mask:0xf bank_mask:0x5
	v_mov_b32_dpp v35, v34 row_shr:4 row_mask:0xf bank_mask:0xa
	v_add_f32_e32 v34, v34, v35
	s_nop 1
	v_mov_b32_dpp v35, v34 row_ror:8 row_mask:0xf bank_mask:0xf
	v_add_f32_e32 v34, v34, v35
	v_mov_b32_e32 v35, v34
	v_mov_b32_e32 v120, v34
	s_nop 1
	v_permlane16_swap_b32_e32 v35, v120
	v_cndmask_b32_e64 v35, v120, v35, s[98:99]
	v_add_f32_e32 v34, v34, v35
	v_mov_b32_e32 v35, v34
	v_mov_b32_e32 v120, v34
	s_nop 1
	v_permlane32_swap_b32_e32 v35, v120
	v_cndmask_b32_e64 v35, v120, v35, s[100:101]
	v_add_f32_e32 v34, v34, v35
	v_fmamk_f32 v34, v34, 0x3a800000, v49
	v_mul_f32_e32 v35, 0x4f800000, v34
	v_cmp_gt_f32_e32 vcc, s31, v34
	s_nop 1
	v_cndmask_b32_e32 v34, v34, v35, vcc
	v_sqrt_f32_e32 v35, v34
	s_nop 0
	v_add_u32_e32 v38, -1, v35
	v_add_u32_e32 v39, 1, v35
	v_fma_f32 v50, -v38, v35, v34
	v_fma_f32 v71, -v39, v35, v34
	v_cmp_ge_f32_e64 s[28:29], 0, v50
	s_nop 1
	v_cndmask_b32_e64 v35, v35, v38, s[28:29]
	v_cmp_lt_f32_e64 s[28:29], 0, v71
	s_nop 1
	v_cndmask_b32_e64 v35, v35, v39, s[28:29]
	v_mul_f32_e32 v38, 0x37800000, v35
	v_cndmask_b32_e32 v35, v35, v38, vcc
	v_cmp_class_f32_e32 vcc, v34, v66
	s_nop 1
	v_cndmask_b32_e32 v34, v35, v34, vcc
	v_div_scale_f32 v35, s[28:29], v34, v34, 1.0
	v_rcp_f32_e32 v38, v35
	v_div_scale_f32 v39, vcc, 1.0, v34, 1.0
	v_fma_f32 v50, -v35, v38, 1.0
	v_fmac_f32_e32 v38, v50, v38
	v_mul_f32_e32 v50, v39, v38
	v_fma_f32 v71, -v35, v50, v39
	v_fmac_f32_e32 v50, v71, v38
	v_fma_f32 v35, -v35, v50, v39
	v_div_fmas_f32 v35, v35, v38, v50
	v_div_fixup_f32 v50, v35, v34, 1.0
	s_and_saveexec_b64 s[28:29], s[10:11]
	s_cbranch_execz .LBB0_1059
	s_ashr_i32 s45, s44, 31
	s_lshl_b64 s[52:53], s[44:45], 2
	s_add_u32 s52, s3, s52
	v_mul_f32_e32 v34, 0x3a800000, v61
	s_addc_u32 s53, s40, s53
	v_mov_b32_e32 v35, v50
	global_store_dwordx2 v51, v[34:35], s[52:53]
; #define LAS __attribute__((address_space(3)))
; __device__ __forceinline__ unsigned pk2(float lo, float hi) { return f2bf(lo) | (f2bf(hi) << 16); }
; template <int SRC, int EXTRA, bool OUT8 = false> ...
;     ...
;         if (stats && lane == 0) { stats[2 * row] = mean; stats[2 * row + 1] = rstd; }
; #pragma unroll
;         for (int j = 0; j < 4; ++j) { v[j] = v[j] * rstd * gv[j] + bv[j]; if (of32) *(f32x4*)(of32 + (size_t)row * 1024 + 256 * j + 4 * lane) = v[j];
;             if (obf) { if constexpr (OUT8) { int w = 0; w = __builtin_amdgcn_cvt_pk_fp8_f32(v[j].x, v[j].y, w, false); w = __builtin_amdgcn_cvt_pk_fp8_f32(v[j].z, v[j].w, w, true); *(unsigned*)((unsigned char*)obf + (size_t)row * 1024 + 256 * j + 4 * lane) = (unsigned)w; }
;                 else { v2u o; o.x = pk2(v[j].x, v[j].y); o.y = pk2(v[j].z, v[j].w); *(v2u*)(obf + (size_t)row * 1024 + 256 * j + 4 * lane) = o; } } }
;         if (EXTRA != 0) {
;             float d[8];
; #pragma unroll
;             for (int e = 0; e < 8; ++e) { float a = 0.f;
; #pragma unroll
;                 for (int j = 0; j < 4; ++j) { const f32x4 w = *(const LAS f32x4*)(w8s + e * 1024 + 256 * j + 4 * lane); a += (v[j].x * w.x + v[j].y * w.y) + (v[j].z * w.z + v[j].w * w.w); }
;                 d[e] = wave_sum(a); }
.LBB0_1059:
	s_or_b64 exec, exec, s[28:29]
	v_pk_mul_f32 v[38:39], v[44:45], v[50:51] op_sel_hi:[1,0]
	v_pk_mul_f32 v[34:35], v[64:65], v[50:51] op_sel_hi:[1,0]
	v_pk_fma_f32 v[38:39], v[0:1], v[38:39], v[8:9]
	v_pk_fma_f32 v[34:35], v[2:3], v[34:35], v[10:11]
	v_bfe_u32 v44, v38, 16, 1
	v_add3_u32 v44, v38, v44, s35
	v_bfe_u32 v45, v39, 16, 1
	v_lshrrev_b32_e32 v44, 16, v44
	v_add3_u32 v45, v39, v45, s35
	v_and_or_b32 v44, v45, s42, v44
	v_bfe_u32 v45, v34, 16, 1
	v_add3_u32 v45, v34, v45, s35
	v_bfe_u32 v61, v35, 16, 1
	v_lshrrev_b32_e32 v45, 16, v45
	v_add3_u32 v61, v35, v61, s35
	v_and_or_b32 v45, v61, s42, v45
	global_store_dwordx2 v[56:57], v[44:45], off offset:-1536
	v_pk_mul_f32 v[42:43], v[42:43], v[50:51] op_sel_hi:[1,0]
	v_pk_mul_f32 v[44:45], v[40:41], v[50:51] op_sel_hi:[1,0]
	v_pk_fma_f32 v[40:41], v[6:7], v[42:43], v[14:15]
	v_pk_fma_f32 v[42:43], v[4:5], v[44:45], v[12:13]
	v_bfe_u32 v61, v41, 16, 1
	v_bfe_u32 v44, v42, 16, 1
	v_add3_u32 v44, v42, v44, s35
	v_bfe_u32 v45, v43, 16, 1
	v_lshrrev_b32_e32 v44, 16, v44
	v_add3_u32 v45, v43, v45, s35
	v_and_or_b32 v44, v45, s42, v44
	v_bfe_u32 v45, v40, 16, 1
	v_add3_u32 v45, v40, v45, s35
	v_lshrrev_b32_e32 v45, 16, v45
	v_add3_u32 v61, v41, v61, s35
	v_and_or_b32 v45, v61, s42, v45
	global_store_dwordx2 v[56:57], v[44:45], off offset:-1024
	v_pk_mul_f32 v[44:45], v[62:63], v[50:51] op_sel_hi:[1,0]
	v_pk_mul_f32 v[62:63], v[36:37], v[50:51] op_sel_hi:[1,0]
	v_pk_fma_f32 v[36:37], v[18:19], v[44:45], v[26:27]
	v_pk_fma_f32 v[44:45], v[16:17], v[62:63], v[24:25]
	v_bfe_u32 v63, v37, 16, 1
	v_bfe_u32 v61, v44, 16, 1
	v_add3_u32 v61, v44, v61, s35
	v_bfe_u32 v62, v45, 16, 1
	v_lshrrev_b32_e32 v61, 16, v61
	v_add3_u32 v62, v45, v62, s35
	v_and_or_b32 v62, v62, s42, v61
	v_bfe_u32 v61, v36, 16, 1
	v_add3_u32 v61, v36, v61, s35
	v_lshrrev_b32_e32 v61, 16, v61
	v_add3_u32 v63, v37, v63, s35
	v_and_or_b32 v63, v63, s42, v61
	global_store_dwordx2 v[56:57], v[62:63], off offset:-512
	v_pk_mul_f32 v[46:47], v[46:47], v[50:51] op_sel_hi:[1,0]
	v_pk_mul_f32 v[62:63], v[32:33], v[50:51] op_sel_hi:[1,0]
	v_pk_fma_f32 v[32:33], v[22:23], v[46:47], v[30:31]
	v_pk_fma_f32 v[46:47], v[20:21], v[62:63], v[28:29]
	v_bfe_u32 v71, v33, 16, 1
	v_bfe_u32 v50, v46, 16, 1
	v_add3_u32 v50, v46, v50, s35
	v_bfe_u32 v61, v47, 16, 1
	v_lshrrev_b32_e32 v50, 16, v50
	v_add3_u32 v61, v47, v61, s35
	v_and_or_b32 v72, v61, s42, v50
	v_bfe_u32 v50, v32, 16, 1
	v_add3_u32 v50, v32, v50, s35
	v_lshrrev_b32_e32 v61, 16, v50
	v_add_u32_e32 v50, 0, v48
	v_add3_u32 v71, v33, v71, s35
	v_and_or_b32 v73, v71, s42, v61
	global_store_dwordx2 v[56:57], v[72:73], off
	s_waitcnt lgkmcnt(0)
	v_pk_mul_f32 v[104:105], v[38:39], v[124:125]
	v_pk_mul_f32 v[106:107], v[38:39], v[140:141]
	v_pk_mul_f32 v[108:109], v[38:39], v[156:157]
	v_pk_mul_f32 v[110:111], v[38:39], v[172:173]
	v_pk_fma_f32 v[104:105], v[34:35], v[126:127], v[104:105]
	v_pk_fma_f32 v[106:107], v[34:35], v[142:143], v[106:107]
	v_pk_fma_f32 v[108:109], v[34:35], v[158:159], v[108:109]
	v_pk_fma_f32 v[110:111], v[34:35], v[174:175], v[110:111]
	ds_read_b128 v[124:127], v48 offset:16384
	ds_read_b128 v[140:143], v48 offset:20480
	ds_read_b128 v[156:159], v48 offset:24576
	ds_read_b128 v[172:175], v48 offset:28672
	v_pk_fma_f32 v[104:105], v[42:43], v[128:129], v[104:105]
	v_pk_fma_f32 v[106:107], v[42:43], v[144:145], v[106:107]
	v_pk_fma_f32 v[108:109], v[42:43], v[160:161], v[108:109]
	v_pk_fma_f32 v[110:111], v[42:43], v[176:177], v[110:111]
	v_pk_fma_f32 v[104:105], v[40:41], v[130:131], v[104:105]
	v_pk_fma_f32 v[106:107], v[40:41], v[146:147], v[106:107]
	v_pk_fma_f32 v[108:109], v[40:41], v[162:163], v[108:109]
	v_pk_fma_f32 v[110:111], v[40:41], v[178:179], v[110:111]
	ds_read_b128 v[128:131], v48 offset:17408
	ds_read_b128 v[144:147], v48 offset:21504
	ds_read_b128 v[160:163], v48 offset:25600
	ds_read_b128 v[176:179], v48 offset:29696
	v_pk_fma_f32 v[104:105], v[44:45], v[132:133], v[104:105]
	v_pk_fma_f32 v[106:107], v[44:45], v[148:149], v[106:107]
	v_pk_fma_f32 v[108:109], v[44:45], v[164:165], v[108:109]
	v_pk_fma_f32 v[110:111], v[44:45], v[180:181], v[110:111]
	v_pk_fma_f32 v[104:105], v[36:37], v[134:135], v[104:105]
	v_pk_fma_f32 v[106:107], v[36:37], v[150:151], v[106:107]
	v_pk_fma_f32 v[108:109], v[36:37], v[166:167], v[108:109]
	v_pk_fma_f32 v[110:111], v[36:37], v[182:183], v[110:111]
	ds_read_b128 v[132:135], v48 offset:18432
	ds_read_b128 v[148:151], v48 offset:22528
	ds_read_b128 v[164:167], v48 offset:26624
	ds_read_b128 v[180:183], v48 offset:30720
	v_pk_fma_f32 v[104:105], v[46:47], v[136:137], v[104:105]
	v_pk_fma_f32 v[106:107], v[46:47], v[152:153], v[106:107]
	v_pk_fma_f32 v[108:109], v[46:47], v[168:169], v[108:109]
	v_pk_fma_f32 v[110:111], v[46:47], v[184:185], v[110:111]
	v_pk_fma_f32 v[104:105], v[32:33], v[138:139], v[104:105]
	v_pk_fma_f32 v[106:107], v[32:33], v[154:155], v[106:107]
	v_pk_fma_f32 v[108:109], v[32:33], v[170:171], v[108:109]
	v_pk_fma_f32 v[110:111], v[32:33], v[186:187], v[110:111]
	ds_read_b128 v[136:139], v48 offset:19456
	ds_read_b128 v[152:155], v48 offset:23552
	ds_read_b128 v[168:171], v48 offset:27648
	ds_read_b128 v[184:187], v48 offset:31744
	v_add_f32_e32 v96, v104, v105
	v_add_f32_e32 v97, v106, v107
	v_add_f32_e32 v98, v108, v109
	v_add_f32_e32 v99, v110, v111
	s_waitcnt lgkmcnt(12)
	v_pk_mul_f32 v[104:105], v[38:39], v[124:125]
	v_pk_mul_f32 v[106:107], v[38:39], v[140:141]
	v_pk_mul_f32 v[108:109], v[38:39], v[156:157]
	v_pk_mul_f32 v[110:111], v[38:39], v[172:173]
	v_pk_fma_f32 v[104:105], v[34:35], v[126:127], v[104:105]
	v_pk_fma_f32 v[106:107], v[34:35], v[142:143], v[106:107]
	v_pk_fma_f32 v[108:109], v[34:35], v[158:159], v[108:109]
	v_pk_fma_f32 v[110:111], v[34:35], v[174:175], v[110:111]
	s_waitcnt lgkmcnt(8)
; #define LAS __attribute__((address_space(3)))
; template <int SRC, int EXTRA, bool OUT8 = false> ...
;     ...
;             for (int e = 0; e < 8; ++e) { float a = 0.f;
; #pragma unroll
;                 for (int j = 0; j < 4; ++j) { const f32x4 w = *(const LAS f32x4*)(w8s + e * 1024 + 256 * j + 4 * lane); a += (v[j].x * w.x + v[j].y * w.y) + (v[j].z * w.z + v[j].w * w.w); }
;                 d[e] = wave_sum(a); }
;             if (EXTRA == 1) {
;                 float x = d[0];
; #pragma unroll
;                 for (int e = 1; e < 8; ++e) x = (lane == e) ? d[e] : x;
;                 if (lane < 8) { x += bf8[lane]; const float ls = (x >= 0.f) ? -log1pf(__expf(-x)) : (x - log1pf(__expf(x))); logf[(size_t)lane * M + row] = ls; }
	v_pk_fma_f32 v[104:105], v[42:43], v[128:129], v[104:105]
	v_pk_fma_f32 v[106:107], v[42:43], v[144:145], v[106:107]
	v_pk_fma_f32 v[108:109], v[42:43], v[160:161], v[108:109]
	v_pk_fma_f32 v[110:111], v[42:43], v[176:177], v[110:111]
	v_pk_fma_f32 v[104:105], v[40:41], v[130:131], v[104:105]
	v_pk_fma_f32 v[106:107], v[40:41], v[146:147], v[106:107]
	v_pk_fma_f32 v[108:109], v[40:41], v[162:163], v[108:109]
	v_pk_fma_f32 v[110:111], v[40:41], v[178:179], v[110:111]
	s_waitcnt lgkmcnt(4)
	v_pk_fma_f32 v[104:105], v[44:45], v[132:133], v[104:105]
	v_pk_fma_f32 v[106:107], v[44:45], v[148:149], v[106:107]
	v_pk_fma_f32 v[108:109], v[44:45], v[164:165], v[108:109]
	v_pk_fma_f32 v[110:111], v[44:45], v[180:181], v[110:111]
	v_pk_fma_f32 v[104:105], v[36:37], v[134:135], v[104:105]
	v_pk_fma_f32 v[106:107], v[36:37], v[150:151], v[106:107]
	v_pk_fma_f32 v[108:109], v[36:37], v[166:167], v[108:109]
	v_pk_fma_f32 v[110:111], v[36:37], v[182:183], v[110:111]
	s_waitcnt lgkmcnt(0)
	v_pk_fma_f32 v[104:105], v[46:47], v[136:137], v[104:105]
	v_pk_fma_f32 v[106:107], v[46:47], v[152:153], v[106:107]
	v_pk_fma_f32 v[108:109], v[46:47], v[168:169], v[108:109]
	v_pk_fma_f32 v[110:111], v[46:47], v[184:185], v[110:111]
	v_pk_fma_f32 v[104:105], v[32:33], v[138:139], v[104:105]
	v_pk_fma_f32 v[106:107], v[32:33], v[154:155], v[106:107]
	v_pk_fma_f32 v[108:109], v[32:33], v[170:171], v[108:109]
	v_pk_fma_f32 v[110:111], v[32:33], v[186:187], v[110:111]
	v_add_f32_e32 v100, v104, v105
	v_add_f32_e32 v101, v106, v107
	v_add_f32_e32 v102, v108, v109
	v_add_f32_e32 v103, v110, v111
	s_nop 0
	v_add_f32_dpp v104, v96, v96 quad_perm:[1,0,3,2] row_mask:0xf bank_mask:0xf
	v_add_f32_dpp v105, v97, v97 quad_perm:[1,0,3,2] row_mask:0xf bank_mask:0xf
	v_cndmask_b32_e64 v112, v104, v105, s[58:59]
	v_add_f32_dpp v106, v98, v98 quad_perm:[1,0,3,2] row_mask:0xf bank_mask:0xf
	v_add_f32_dpp v107, v99, v99 quad_perm:[1,0,3,2] row_mask:0xf bank_mask:0xf
	v_cndmask_b32_e64 v113, v106, v107, s[58:59]
	v_add_f32_dpp v108, v100, v100 quad_perm:[1,0,3,2] row_mask:0xf bank_mask:0xf
	v_add_f32_dpp v109, v101, v101 quad_perm:[1,0,3,2] row_mask:0xf bank_mask:0xf
	v_cndmask_b32_e64 v114, v108, v109, s[58:59]
	v_add_f32_dpp v110, v102, v102 quad_perm:[1,0,3,2] row_mask:0xf bank_mask:0xf
	v_add_f32_dpp v111, v103, v103 quad_perm:[1,0,3,2] row_mask:0xf bank_mask:0xf
	v_cndmask_b32_e64 v115, v110, v111, s[58:59]
	v_add_f32_dpp v104, v112, v112 quad_perm:[2,3,0,1] row_mask:0xf bank_mask:0xf
	v_add_f32_dpp v105, v113, v113 quad_perm:[2,3,0,1] row_mask:0xf bank_mask:0xf
	v_cndmask_b32_e64 v116, v104, v105, s[60:61]
	v_add_f32_dpp v106, v114, v114 quad_perm:[2,3,0,1] row_mask:0xf bank_mask:0xf
	v_add_f32_dpp v107, v115, v115 quad_perm:[2,3,0,1] row_mask:0xf bank_mask:0xf
	v_cndmask_b32_e64 v117, v106, v107, s[60:61]
	v_add_f32_dpp v104, v116, v116 row_shl:4 row_mask:0xf bank_mask:0x5
	v_add_f32_dpp v104, v116, v116 row_shr:4 row_mask:0xf bank_mask:0xa
	v_add_f32_dpp v105, v117, v117 row_shl:4 row_mask:0xf bank_mask:0x5
	v_add_f32_dpp v105, v117, v117 row_shr:4 row_mask:0xf bank_mask:0xa
	v_cndmask_b32_e64 v118, v104, v105, s[62:63]
	s_nop 1
	v_add_f32_dpp v119, v118, v118 row_ror:8 row_mask:0xf bank_mask:0xf
	v_mov_b32_e32 v104, v119
	v_mov_b32_e32 v120, v119
	s_nop 1
	v_permlane16_swap_b32_e32 v104, v120
	v_cndmask_b32_e64 v104, v120, v104, s[98:99]
	v_add_f32_e32 v119, v119, v104
	v_mov_b32_e32 v104, v119
	v_mov_b32_e32 v120, v119
	s_nop 1
	v_permlane32_swap_b32_e32 v104, v120
	v_cndmask_b32_e64 v104, v120, v104, s[100:101]
	v_add_f32_e32 v32, v119, v104
	s_and_saveexec_b64 s[28:29], s[12:13]
	s_cbranch_execz .LBB0_1056
	v_add_f32_e32 v32, v32, v206
	v_cmp_le_f32_e32 vcc, 0, v32
	s_and_saveexec_b64 s[52:53], vcc
	s_xor_b64 s[52:53], exec, s[52:53]
	s_cbranch_execz .LBB0_1062
; template <int SRC, int EXTRA, bool OUT8 = false> ...
;     ...
;             if (EXTRA == 1) {
;                 float x = d[0];
; #pragma unroll
;                 for (int e = 1; e < 8; ++e) x = (lane == e) ? d[e] : x;
;                 if (lane < 8) { x += bf8[lane]; const float ls = (x >= 0.f) ? -log1pf(__expf(-x)) : (x - log1pf(__expf(x))); logf[(size_t)lane * M + row] = ls; }
	v_mul_f32_e32 v32, 0xbfb8aa3b, v32
	v_exp_f32_e32 v46, v32
	s_nop 0
	v_add_f32_e32 v34, 1.0, v46
	v_frexp_mant_f32_e32 v36, v34
	v_cvt_f64_f32_e32 v[32:33], v34
	v_frexp_exp_i32_f64_e32 v32, v[32:33]
	v_cmp_gt_f32_e32 vcc, s43, v36
	v_add_f32_e32 v35, -1.0, v34
	v_sub_f32_e32 v37, v35, v34
	v_subbrev_co_u32_e32 v40, vcc, 0, v32, vcc
	v_sub_u32_e32 v32, 0, v40
	v_sub_f32_e32 v35, v46, v35
	v_add_f32_e32 v37, 1.0, v37
	v_ldexp_f32 v33, v34, v32
	v_add_f32_e32 v35, v35, v37
	v_add_f32_e32 v34, -1.0, v33
	v_add_f32_e32 v36, 1.0, v33
	v_ldexp_f32 v32, v35, v32
	v_add_f32_e32 v35, 1.0, v34
	v_add_f32_e32 v37, -1.0, v36
	v_sub_f32_e32 v35, v33, v35
	v_sub_f32_e32 v33, v33, v37
	v_add_f32_e32 v35, v32, v35
	v_add_f32_e32 v32, v32, v33
	v_add_f32_e32 v41, v36, v32
	v_rcp_f32_e32 v43, v41
	v_sub_f32_e32 v33, v41, v36
	v_sub_f32_e32 v42, v32, v33
	v_add_f32_e32 v33, v34, v35
	v_mul_f32_e32 v45, v33, v43
	v_sub_f32_e32 v32, v33, v34
	v_mul_f32_e32 v34, v41, v45
	v_fma_f32 v36, v45, v41, -v34
	v_fmac_f32_e32 v36, v45, v42
	v_sub_f32_e32 v44, v35, v32
	v_add_f32_e32 v32, v34, v36
	v_sub_f32_e32 v35, v33, v32
	v_pk_add_f32 v[38:39], v[32:33], v[34:35] neg_lo:[0,1] neg_hi:[0,1]
	v_mov_b32_e32 v37, v32
	v_pk_add_f32 v[32:33], v[38:39], v[36:37] neg_lo:[0,1] neg_hi:[0,1]
	v_cmp_neq_f32_e32 vcc, s55, v46
	v_add_f32_e32 v33, v44, v33
	v_add_f32_e32 v32, v32, v33
	v_add_f32_e32 v33, v35, v32
	v_mul_f32_e32 v44, v43, v33
	v_mul_f32_e32 v34, v41, v44
	v_fma_f32 v36, v44, v41, -v34
	v_fmac_f32_e32 v36, v44, v42
	v_sub_f32_e32 v35, v35, v33
	v_add_f32_e32 v41, v32, v35
	v_add_f32_e32 v32, v34, v36
	v_sub_f32_e32 v35, v33, v32
	v_pk_add_f32 v[38:39], v[32:33], v[34:35] neg_lo:[0,1] neg_hi:[0,1]
	v_mov_b32_e32 v37, v32
	v_pk_add_f32 v[32:33], v[38:39], v[36:37] neg_lo:[0,1] neg_hi:[0,1]
	s_nop 0
	v_add_f32_e32 v33, v41, v33
	v_add_f32_e32 v32, v32, v33
	v_add_f32_e32 v33, v45, v44
	v_add_f32_e32 v32, v35, v32
	v_sub_f32_e32 v34, v33, v45
	v_mul_f32_e32 v32, v43, v32
	v_sub_f32_e32 v34, v44, v34
	v_add_f32_e32 v34, v34, v32
	v_add_f32_e32 v36, v33, v34
	v_mul_f32_e32 v37, v36, v36
	v_fmamk_f32 v32, v37, 0x3e9b6dac, v67
	v_fmaak_f32 v61, v37, v32, 0x3f2aaada
	v_cvt_f32_i32_e32 v32, v40
	v_sub_f32_e32 v33, v36, v33
	v_sub_f32_e32 v33, v34, v33
	v_ldexp_f32 v38, v33, 1
	v_mul_f32_e32 v33, v36, v37
	v_ldexp_f32 v35, v36, 1
	v_pk_mul_f32 v[36:37], v[32:33], v[60:61]
	s_nop 0
	v_fma_f32 v34, v32, s54, -v36
	v_fmac_f32_e32 v34, 0xb102e308, v32
	v_pk_add_f32 v[32:33], v[36:37], v[34:35]
	s_nop 0
	v_sub_f32_e32 v35, v33, v35
	v_sub_f32_e32 v35, v37, v35
	v_add_f32_e32 v39, v38, v35
	v_mov_b32_e32 v38, v36
	v_pk_add_f32 v[36:37], v[32:33], v[36:37] neg_lo:[0,1] neg_hi:[0,1]
	v_pk_add_f32 v[40:41], v[32:33], v[38:39]
	v_mov_b32_e32 v35, v32
	v_mov_b32_e32 v37, v41
	v_pk_add_f32 v[42:43], v[34:35], v[36:37] neg_lo:[0,1] neg_hi:[0,1]
	v_pk_add_f32 v[34:35], v[34:35], v[36:37]
	v_mov_b32_e32 v38, v39
	v_pk_add_f32 v[36:37], v[34:35], v[32:33] op_sel:[1,0] op_sel_hi:[0,1] neg_lo:[0,1] neg_hi:[0,1]
	v_pk_add_f32 v[44:45], v[40:41], v[36:37] op_sel_hi:[1,0] neg_lo:[0,1] neg_hi:[0,1]
	v_mov_b32_e32 v40, v41
	v_mov_b32_e32 v41, v35
	v_pk_mov_b32 v[36:37], v[32:33], v[36:37] op_sel:[1,0]
	v_mov_b32_e32 v39, v32
	v_pk_add_f32 v[36:37], v[40:41], v[36:37] neg_lo:[0,1] neg_hi:[0,1]
	v_mov_b32_e32 v44, v42
	v_pk_add_f32 v[32:33], v[38:39], v[36:37] neg_lo:[0,1] neg_hi:[0,1]
	v_mov_b32_e32 v43, v35
	v_pk_add_f32 v[36:37], v[44:45], v[32:33]
	s_nop 0
	v_pk_add_f32 v[38:39], v[36:37], v[36:37] op_sel:[0,1] op_sel_hi:[1,0]
	s_nop 0
	v_pk_add_f32 v[34:35], v[34:35], v[38:39] op_sel:[1,0] op_sel_hi:[0,1]
	v_mov_b32_e32 v37, v34
	v_pk_add_f32 v[40:41], v[36:37], v[42:43] neg_lo:[0,1] neg_hi:[0,1]
	v_mov_b32_e32 v33, v38
	v_sub_f32_e32 v35, v36, v40
	v_pk_add_f32 v[32:33], v[32:33], v[40:41] neg_lo:[0,1] neg_hi:[0,1]
	v_sub_f32_e32 v35, v42, v35
	v_add_f32_e32 v32, v32, v35
	v_add_f32_e32 v32, v32, v33
	v_add_f32_e32 v32, v34, v32
	v_cndmask_b32_e32 v32, v68, v32, vcc
	v_cmp_ngt_f32_e32 vcc, -1.0, v46
	s_nop 1
	v_cndmask_b32_e32 v32, v69, v32, vcc
	v_cmp_neq_f32_e32 vcc, -1.0, v46
	s_nop 1
	v_cndmask_b32_e32 v32, v70, v32, vcc
	v_cmp_lt_f32_e64 vcc, |v46|, s56
	s_nop 1
	v_cndmask_b32_e32 v32, v32, v46, vcc
	v_xor_b32_e32 v33, 0x80000000, v32

; __device__ __forceinline__ int mk_tid(int wv) { return (wv << 6) | lane_now(); }
; #define LAS __attribute__((address_space(3)))
; template <int SRC, int EXTRA, bool OUT8 = false> ...
;     const int tid = mk_tid(wv); const int lane = tid & 63, wave = wv;
;     LAS float* w8s = (LAS float*)lds;
;     LAS unsigned* lcnt = (LAS unsigned*)(lds + 32768);
;     if (EXTRA != 0) { for (int i = tid; i < 8192; i += NT) { const int k = i >> 3, j = i & 7; w8s[j * 1024 + k] = w8[(size_t)k * w8ld + j]; } if (tid < 8) lcnt[tid] = 0u; __syncthreads(); }
;     f32x4 gv[4], bv[4];
; #pragma unroll
;     for (int j = 0; j < 4; ++j) { gv[j] = *(const f32x4*)(g + 256 * j + 4 * lane); bv[j] = *(const f32x4*)(b + 256 * j + 4 * lane); }
;     const int gw = blockIdx.x * NWAVES + wave, NGW = G * NWAVES;
;     for (int row = gw; row < M; row += NGW) {
.LBB0_1891:
	s_or_b64 exec, exec, s[8:9]
	v_cmp_gt_i32_e64 s[8:9], 8, v48
	v_lshl_add_u32 v49, v48, 2, 0
	s_and_saveexec_b64 s[24:25], s[8:9]
	v_mov_b32_e32 v0, 0
	ds_write_b32 v49, v0 offset:32768
	s_or_b64 exec, exec, s[24:25]
	s_and_b64 vcc, exec, s[4:5]
	s_waitcnt lgkmcnt(0)
	s_barrier
	s_cbranch_vccnz .LBB0_1900
	v_and_b32_e32 v38, 63, v4
	v_lshlrev_b32_e32 v50, 4, v38
	v_mov_b32_e32 v51, 0
	v_lshl_add_u64 v[0:1], s[20:21], 0, v[50:51]
	s_mov_b64 s[20:21], 0x1000
	v_lshl_add_u64 v[32:33], v[0:1], 0, s[20:21]
	v_add_co_u32_e32 v0, vcc, 0x1000, v0
	v_lshl_add_u64 v[4:5], s[22:23], 0, v[50:51]
	s_nop 0
	v_addc_co_u32_e32 v1, vcc, 0, v1, vcc
	v_add_co_u32_e32 v36, vcc, 0x1000, v4
	v_lshl_add_u64 v[34:35], v[4:5], 0, s[20:21]
	s_nop 0
	v_addc_co_u32_e32 v37, vcc, 0, v5, vcc
	global_load_dwordx4 v[0:3], v[0:1], off
	s_nop 0
	global_load_dwordx4 v[4:7], v[36:37], off
	global_load_dwordx4 v[8:11], v[32:33], off offset:1024
	global_load_dwordx4 v[12:15], v[32:33], off offset:2048
	global_load_dwordx4 v[16:19], v[34:35], off offset:1024
	global_load_dwordx4 v[20:23], v[34:35], off offset:2048
	global_load_dwordx4 v[24:27], v[32:33], off offset:3072
	global_load_dwordx4 v[28:31], v[34:35], off offset:3072
	s_add_u32 s3, s10, 0x400000
	s_addc_u32 s50, s11, 0
	s_add_u32 s51, s18, 0x340000
	s_addc_u32 s52, s19, 0
	s_lshl_b32 s18, s2, 4
	s_lshl_b32 s19, s68, 1
	s_ashr_i32 s35, s34, 31
	s_add_i32 s38, s18, s19
	s_lshl_b32 s53, s33, 4
	s_lshl_b64 s[18:19], s[34:35], 2
	s_add_u32 s16, s16, s18
	s_addc_u32 s17, s17, s19
	s_add_u32 s40, s16, 0x300000
	s_addc_u32 s41, s17, 0
	s_ashr_i32 s31, s30, 31
	s_lshl_b64 s[42:43], s[30:31], 2
	s_lshl_b64 s[16:17], s[34:35], 11
	s_add_u32 s14, s14, s16
	v_lshlrev_b32_e32 v32, 3, v38
	v_mov_b32_e32 v33, v51
	s_addc_u32 s15, s15, s17
	v_lshl_add_u64 v[32:33], s[14:15], 0, v[32:33]
	s_mov_b64 s[14:15], 0x12500600
	v_lshl_add_u64 v[52:53], v[32:33], 0, s[14:15]
	s_lshl_b64 s[44:45], s[30:31], 11
	s_lshl_b64 s[14:15], s[34:35], 12
	s_add_u32 s12, s12, s14
	s_addc_u32 s13, s13, s15
	v_lshl_add_u64 v[32:33], s[12:13], 0, v[50:51]
	s_mov_b64 s[12:13], 0x28500c00
	v_cmp_eq_u32_e64 s[10:11], 0, v38
	v_lshl_add_u64 v[54:55], v[32:33], 0, s[12:13]
	s_lshl_b64 s[46:47], s[30:31], 12
	v_mov_b32_e32 v61, 0x3727c5ac
	s_mov_b32 s31, 0xf800000
	v_mov_b32_e32 v62, 0x260
	s_movk_i32 s35, 0x7fff
	s_mov_b32 s54, 0xffff0000
	v_mov_b32_e32 v63, 1
	s_mov_b32 s55, 0xff800000
	v_mov_b32_e32 v64, 0xff800000
	s_mov_b32 s56, s34
	global_load_dwordx4 v[200:203], v[54:55], off offset:-3072
	global_load_dwordx4 v[196:199], v[54:55], off offset:-2048
	global_load_dwordx4 v[192:195], v[54:55], off offset:-1024
	global_load_dwordx4 v[188:191], v[54:55], off
	s_waitcnt vmcnt(0)
	s_branch .LBB0_1896

; template <int SRC, int EXTRA, bool OUT8 = false> ...
;     ...
;     for (int row = gw; row < M; row += NGW) {
;         f32x4 v[4];
;         if (SRC == 0) {
; #pragma unroll
;             for (int j = 0; j < 4; ++j) v[j] = *(const f32x4*)(src + (size_t)row * 1024 + 256 * j + 4 * lane);
;         } else {
;             const int p0 = pos[2 * row], p1 = pos[2 * row + 1]; const float w0 = gwt[2 * row], w1 = gwt[2 * row + 1]; const float hm = hp.stats[2 * row], hr = hp.stats[2 * row + 1];
; #pragma unroll
;             for (int j = 0; j < 4; ++j) { const f32x4 a = (*(const f32x4*)(hp.src + (size_t)row * 1024 + 256 * j + 4 * lane) - hm) * hr * *(const f32x4*)(hp.g + 256 * j + 4 * lane) + *(const f32x4*)(hp.b + 256 * j + 4 * lane);
;                 f32x4 y[2];
; #pragma unroll
;                 for (int q = 0; q < 2; ++q) { const int p = q ? p1 : p0; const int t = __builtin_amdgcn_readfirstlane(tailid[(p >> 8) * 4 + j]);
;                     if (t < 0) y[q] = *(const f32x4*)(ys + (size_t)p * 1024 + 256 * j + 4 * lane);
;                     else { f32x4 acc = (f32x4){0.f, 0.f, 0.f, 0.f};
; #pragma unroll
;                         for (int sl = 0; sl < 7; ++sl) acc = acc + *(const f32x4*)(part + ((size_t)(t * 7 + sl) * 256 + (p & 255)) * 256 + 4 * lane);
;                         y[q] = acc; } }
;                 v[j] = a * ALPHA + y[0] * w0 + y[1] * w1; }
;         }
;         float s = 0.f;
; #pragma unroll
;         for (int j = 0; j < 4; ++j) s += (v[j].x + v[j].y) + (v[j].z + v[j].w);
;         const float mean = wave_sum(s) * (1.f / 1024.f); float s2 = 0.f;
; #pragma unroll
;         for (int j = 0; j < 4; ++j) { v[j] = v[j] - mean; s2 += (v[j].x * v[j].x + v[j].y * v[j].y) + (v[j].z * v[j].z + v[j].w * v[j].w); }
;         const float rstd = 1.f / sqrtf(wave_sum(s2) * (1.f / 1024.f) + LN_EPS);
;         if (stats && lane == 0) { stats[2 * row] = mean; stats[2 * row + 1] = rstd; }
.LBB0_1896:
	s_waitcnt vmcnt(2)
	v_mov_b64_e32 v[32:33], v[188:189]
	v_mov_b64_e32 v[34:35], v[190:191]
	v_mov_b64_e32 v[36:37], v[192:193]
	v_mov_b64_e32 v[38:39], v[194:195]
	v_mov_b64_e32 v[40:41], v[196:197]
	v_mov_b64_e32 v[42:43], v[198:199]
	v_mov_b64_e32 v[44:45], v[200:201]
	v_mov_b64_e32 v[46:47], v[202:203]
	s_add_i32 s95, s56, s30
	s_cmpk_lt_i32 s95, 0x4000
	s_cbranch_scc0 .Lrowpf_48034
	v_lshl_add_u64 v[204:205], v[54:55], 0, s[46:47]
	global_load_dwordx4 v[200:203], v[204:205], off offset:-3072
	global_load_dwordx4 v[196:199], v[204:205], off offset:-2048
	global_load_dwordx4 v[192:195], v[204:205], off offset:-1024
	global_load_dwordx4 v[188:191], v[204:205], off
.Lrowpf_48034:
	s_waitcnt lgkmcnt(0)
	v_mov_b32_e32 v57, v46
	v_mov_b32_e32 v56, v45
	v_mov_b32_e32 v58, v44
	v_mov_b32_e32 v59, v47
	v_mov_b32_e32 v66, v41
	v_mov_b32_e32 v67, v42
	v_mov_b32_e32 v68, v40
	v_mov_b32_e32 v69, v43
	v_pk_add_f32 v[56:57], v[56:57], v[58:59]
	v_pk_add_f32 v[58:59], v[66:67], v[68:69]
	v_add_f32_e32 v65, v56, v57
	v_pk_add_f32 v[56:57], v[58:59], v[58:59] op_sel:[0,1] op_sel_hi:[1,0]
	v_add_f32_e32 v70, v36, v37
	v_add_f32_e32 v72, v38, v39
	v_mov_b32_e32 v75, v32
	v_mov_b32_e32 v71, v34
	v_mov_b32_e32 v73, v35
	v_add_f32_e32 v74, 0, v65
	v_mov_b32_e32 v57, v33
	v_pk_add_f32 v[66:67], v[70:71], v[72:73]
	v_pk_add_f32 v[56:57], v[74:75], v[56:57]
	s_nop 0
	v_pk_add_f32 v[56:57], v[56:57], v[66:67]
	v_add_f32_e32 v56, v56, v57
	s_nop 1
	v_mov_b32_dpp v57, v56 quad_perm:[1,0,3,2] row_mask:0xf bank_mask:0xf
	v_add_f32_e32 v56, v56, v57
	s_nop 1
	v_mov_b32_dpp v57, v56 quad_perm:[2,3,0,1] row_mask:0xf bank_mask:0xf
	v_add_f32_e32 v56, v56, v57
	s_nop 1
	v_mov_b32_dpp v57, v56 row_shl:4 row_mask:0xf bank_mask:0x5
	v_mov_b32_dpp v57, v56 row_shr:4 row_mask:0xf bank_mask:0xa
	v_add_f32_e32 v56, v56, v57
	s_nop 1
	v_mov_b32_dpp v57, v56 row_ror:8 row_mask:0xf bank_mask:0xf
	v_add_f32_e32 v56, v56, v57
	v_mov_b32_e32 v57, v56
	v_mov_b32_e32 v120, v56
	s_nop 1
	v_permlane16_swap_b32_e32 v57, v120
	v_cndmask_b32_e64 v57, v120, v57, s[98:99]
	v_add_f32_e32 v56, v56, v57
	v_mov_b32_e32 v57, v56
	v_mov_b32_e32 v120, v56
	s_nop 1
	v_permlane32_swap_b32_e32 v57, v120
	v_cndmask_b32_e64 v57, v120, v57, s[100:101]
	v_add_f32_e32 v65, v56, v57
	v_fmamk_f32 v59, v65, 0xba800000, v47
	v_fmamk_f32 v45, v65, 0xba800000, v45
	v_fmamk_f32 v43, v65, 0xba800000, v43
	v_fmamk_f32 v41, v65, 0xba800000, v41
	v_fmamk_f32 v58, v65, 0xba800000, v46
	v_fmac_f32_e32 v44, 0xba800000, v65
	v_fmamk_f32 v42, v65, 0xba800000, v42
	v_fmac_f32_e32 v40, 0xba800000, v65
	v_fmamk_f32 v57, v65, 0xba800000, v39
	v_fmamk_f32 v56, v65, 0xba800000, v38
	v_fmamk_f32 v37, v65, 0xba800000, v37
	v_fmamk_f32 v47, v65, 0xba800000, v35
	v_fmamk_f32 v46, v65, 0xba800000, v34
	v_mul_f32_e32 v34, v45, v45
	v_mul_f32_e32 v35, v59, v59
	v_mul_f32_e32 v38, v41, v41
	v_mul_f32_e32 v39, v43, v43
	v_fmac_f32_e32 v36, 0xba800000, v65
	v_fmamk_f32 v33, v65, 0xba800000, v33
	v_mul_f32_e32 v66, v37, v37
	v_mul_f32_e32 v67, v57, v57
	v_fmac_f32_e32 v34, v44, v44
	v_fmac_f32_e32 v35, v58, v58
	v_fmac_f32_e32 v38, v40, v40
	v_fmac_f32_e32 v39, v42, v42
	v_fmac_f32_e32 v32, 0xba800000, v65
	v_mul_f32_e32 v68, v33, v33
	v_mul_f32_e32 v69, v47, v47
	v_fmac_f32_e32 v66, v36, v36
	v_fmac_f32_e32 v67, v56, v56
	v_add_f32_e32 v34, v34, v35
	v_add_f32_e32 v35, v38, v39
	v_fmac_f32_e32 v68, v32, v32
	v_fmac_f32_e32 v69, v46, v46
	v_add_f32_e32 v38, v66, v67
	v_add_f32_e32 v34, v34, v35
	v_add_f32_e32 v39, v68, v69
	v_add_f32_e32 v34, v38, v34
	v_add_f32_e32 v34, v39, v34
	s_nop 1
	v_mov_b32_dpp v35, v34 quad_perm:[1,0,3,2] row_mask:0xf bank_mask:0xf
	v_add_f32_e32 v34, v34, v35
	s_nop 1
	v_mov_b32_dpp v35, v34 quad_perm:[2,3,0,1] row_mask:0xf bank_mask:0xf
	v_add_f32_e32 v34, v34, v35
	s_nop 1
	v_mov_b32_dpp v35, v34 row_shl:4 row_mask:0xf bank_mask:0x5
	v_mov_b32_dpp v35, v34 row_shr:4 row_mask:0xf bank_mask:0xa
	v_add_f32_e32 v34, v34, v35
	s_nop 1
	v_mov_b32_dpp v35, v34 row_ror:8 row_mask:0xf bank_mask:0xf
	v_add_f32_e32 v34, v34, v35
	v_mov_b32_e32 v35, v34
	v_mov_b32_e32 v120, v34
	s_nop 1
	v_permlane16_swap_b32_e32 v35, v120
	v_cndmask_b32_e64 v35, v120, v35, s[98:99]
	v_add_f32_e32 v34, v34, v35
	v_mov_b32_e32 v35, v34
	v_mov_b32_e32 v120, v34
	s_nop 1
	v_permlane32_swap_b32_e32 v35, v120
	v_cndmask_b32_e64 v35, v120, v35, s[100:101]
	v_add_f32_e32 v34, v34, v35
	v_fmamk_f32 v34, v34, 0x3a800000, v61
	v_mul_f32_e32 v35, 0x4f800000, v34
	v_cmp_gt_f32_e32 vcc, s31, v34
	s_nop 1
	v_cndmask_b32_e32 v34, v34, v35, vcc
	v_sqrt_f32_e32 v35, v34
	s_nop 0
	v_add_u32_e32 v38, -1, v35
	v_add_u32_e32 v39, 1, v35
	v_fma_f32 v60, -v38, v35, v34
	v_fma_f32 v66, -v39, v35, v34
	v_cmp_ge_f32_e64 s[12:13], 0, v60
	s_nop 1
	v_cndmask_b32_e64 v35, v35, v38, s[12:13]
	v_cmp_lt_f32_e64 s[12:13], 0, v66
	s_nop 1
	v_cndmask_b32_e64 v35, v35, v39, s[12:13]
	v_mul_f32_e32 v38, 0x37800000, v35
	v_cndmask_b32_e32 v35, v35, v38, vcc
	v_cmp_class_f32_e32 vcc, v34, v62
	s_nop 1
	v_cndmask_b32_e32 v34, v35, v34, vcc
	v_div_scale_f32 v35, s[12:13], v34, v34, 1.0
	v_rcp_f32_e32 v38, v35
	v_div_scale_f32 v39, vcc, 1.0, v34, 1.0
	v_fma_f32 v60, -v35, v38, 1.0
	v_fmac_f32_e32 v38, v60, v38
	v_mul_f32_e32 v60, v39, v38
	v_fma_f32 v66, -v35, v60, v39
	v_fmac_f32_e32 v60, v66, v38
	v_fma_f32 v35, -v35, v60, v39
	v_div_fmas_f32 v35, v35, v38, v60
	v_div_fixup_f32 v60, v35, v34, 1.0
	s_and_saveexec_b64 s[12:13], s[10:11]
	s_cbranch_execz .LBB0_1898
	s_ashr_i32 s39, s38, 31
	s_lshl_b64 s[14:15], s[38:39], 2
	s_add_u32 s14, s3, s14
	v_mul_f32_e32 v34, 0x3a800000, v65
	s_addc_u32 s15, s50, s15
	v_mov_b32_e32 v35, v60
	global_store_dwordx2 v51, v[34:35], s[14:15]
